# v18
# baseline (speedup 1.0000x reference)
; #define PG8_STAGE(bufoff, gbase, voff) do { const __amdgpu_buffer_rsrc_t _rs = __builtin_amdgcn_make_buffer_rsrc((void*)(gbase), 0, 0x7fffffff, 0x00020000); _Pragma("unroll") for (int _i = 0; _i < 2; ++_i) \
;         __builtin_amdgcn_raw_ptr_buffer_load_lds(_rs, (LAS unsigned*)(lds + (bufoff) + ldsw + _i * 8192), 16, (int)(voff)[_i], 0, 0, 0); } while (0)
; #define PG8_WAIT_V(n) asm volatile("s_waitcnt vmcnt(" #n ")" ::: "memory")
; #define PG8_WAIT_L(n) asm volatile("s_waitcnt lgkmcnt(" #n ")" ::: "memory")
; #define PG8_BAR __builtin_amdgcn_s_barrier()
; #define PG8_SCHED __builtin_amdgcn_sched_barrier(0)
; template <class Epi, class Sched, bool F8 = false>
; __device__ __forceinline__ void gemm_phase(LAS unsigned char* lds, const int lda, const int ldb, const Sched& S, const Epi& E) {
;     ...
;             const bool last = (t == nt - 2);
;             const char* a1 = cA + (size_t)(t + 1) * kstep;
;             const char* a2 = last ? nA : cA + (size_t)(t + 2) * kstep; const char* b2 = last ? nB : cB + (size_t)(t + 2) * kstepB;
;             const char* a3 = a2 + kstep; const char* b3 = b2 + kstepB;
;     ...
;             PG8_LDB(B0, 0, 0); PG8_LDB(B1, 0, 1); PG8_SCHED; PG8_LDA(At, 0, 0); PG8_STAGE(PG8_SA(1, 1), a1 + hstepA, voffA);
;             PG8_WAIT_V(8); PG8_WAIT_L(0); PG8_BAR; PG8_MMA(0, 0, At, B0); PG8_MMA(0, 1, At, B1); PG8_BAR; PG8_SCHED;
;             PG8_LDA(At, 0, 1); PG8_STAGE(PG8_SB(0, 0), b2, voffB); PG8_STAGE(PG8_SB(0, 1), b2 + hstepB, voffB); PG8_STAGE(PG8_SA(0, 0), a2, voffA);
;             PG8_WAIT_V(8); PG8_WAIT_L(0); PG8_BAR; PG8_MMA(1, 0, At, B0); PG8_MMA(1, 1, At, B1); PG8_BAR; PG8_SCHED;
.LBB0_116:
	ds_read_b128 v[132:135], v140
	ds_read_b128 v[146:149], v140 offset:1024
	ds_read_b128 v[150:153], v140 offset:2048
	ds_read_b128 v[154:157], v140 offset:3072
	ds_read_b128 v[158:161], v141
	ds_read_b128 v[162:165], v141 offset:1024
	ds_read_b128 v[166:169], v141 offset:2048
	ds_read_b128 v[174:177], v141 offset:3072
	s_add_u32 s16, s63, 0xfff00080
	s_addc_u32 s17, s67, -1
	s_cmp_eq_u32 s69, 60
	s_cselect_b32 s28, s70, s16
	s_cselect_b32 s23, s71, s17
	s_cselect_b32 s22, s73, s62
	s_cselect_b32 s24, s72, s7
	s_add_u32 s20, s28, 0x80
	s_addc_u32 s21, s23, 0
	s_and_b32 s17, s67, 0xffff
	s_mov_b32 s16, s63
	s_mov_b32 m0, s93
	ds_read_b128 v[178:181], v142
	ds_read_b128 v[182:185], v142 offset:1024
	ds_read_b128 v[186:189], v142 offset:2048
	ds_read_b128 v[190:193], v142 offset:3072
	ds_read_b128 v[194:197], v142 offset:4096
	ds_read_b128 v[198:201], v142 offset:5120
	ds_read_b128 v[202:205], v142 offset:6144
	ds_read_b128 v[206:209], v142 offset:7168
	buffer_load_dwordx4 v136, s[16:19], 0 offen lds
	s_mov_b32 m0, s94
	s_nop 0
	buffer_load_dwordx4 v138, s[16:19], 0 offen lds
	s_waitcnt vmcnt(8)
	s_waitcnt lgkmcnt(0)
	s_barrier
	s_setprio 1
	v_mfma_f32_16x16x32_bf16 v[124:127], v[132:135], v[178:181], v[124:127]
	v_mfma_f32_16x16x32_bf16 v[120:123], v[150:153], v[178:181], v[120:123]
	v_mfma_f32_16x16x32_bf16 v[108:111], v[132:135], v[186:189], v[108:111]
	v_mfma_f32_16x16x32_bf16 v[104:107], v[150:153], v[186:189], v[104:107]
	v_mfma_f32_16x16x32_bf16 v[92:95], v[132:135], v[194:197], v[92:95]
	v_mfma_f32_16x16x32_bf16 v[88:91], v[150:153], v[194:197], v[88:91]
	v_mfma_f32_16x16x32_bf16 v[76:79], v[132:135], v[202:205], v[76:79]
	v_mfma_f32_16x16x32_bf16 v[72:75], v[150:153], v[202:205], v[72:75]
	v_mfma_f32_16x16x32_bf16 v[124:127], v[146:149], v[182:185], v[124:127]
	v_mfma_f32_16x16x32_bf16 v[120:123], v[154:157], v[182:185], v[120:123]
	v_mfma_f32_16x16x32_bf16 v[108:111], v[146:149], v[190:193], v[108:111]
	v_mfma_f32_16x16x32_bf16 v[104:107], v[154:157], v[190:193], v[104:107]
	v_mfma_f32_16x16x32_bf16 v[92:95], v[146:149], v[198:201], v[92:95]
	v_mfma_f32_16x16x32_bf16 v[88:91], v[154:157], v[198:201], v[88:91]
	v_mfma_f32_16x16x32_bf16 v[76:79], v[146:149], v[206:209], v[76:79]
	v_mfma_f32_16x16x32_bf16 v[72:75], v[154:157], v[206:209], v[72:75]
	v_mfma_f32_16x16x32_bf16 v[116:119], v[158:161], v[178:181], v[116:119]
	v_mfma_f32_16x16x32_bf16 v[112:115], v[166:169], v[178:181], v[112:115]
	v_mfma_f32_16x16x32_bf16 v[100:103], v[158:161], v[186:189], v[100:103]
	v_mfma_f32_16x16x32_bf16 v[96:99], v[166:169], v[186:189], v[96:99]
	v_mfma_f32_16x16x32_bf16 v[84:87], v[158:161], v[194:197], v[84:87]
	v_mfma_f32_16x16x32_bf16 v[80:83], v[166:169], v[194:197], v[80:83]
	v_mfma_f32_16x16x32_bf16 v[68:71], v[158:161], v[202:205], v[68:71]
	v_mfma_f32_16x16x32_bf16 v[64:67], v[166:169], v[202:205], v[64:67]
	v_mfma_f32_16x16x32_bf16 v[116:119], v[162:165], v[182:185], v[116:119]
	v_mfma_f32_16x16x32_bf16 v[112:115], v[174:177], v[182:185], v[112:115]
	v_mfma_f32_16x16x32_bf16 v[100:103], v[162:165], v[190:193], v[100:103]
	v_mfma_f32_16x16x32_bf16 v[96:99], v[174:177], v[190:193], v[96:99]
	v_mfma_f32_16x16x32_bf16 v[84:87], v[162:165], v[198:201], v[84:87]
	v_mfma_f32_16x16x32_bf16 v[80:83], v[174:177], v[198:201], v[80:83]
	v_mfma_f32_16x16x32_bf16 v[68:71], v[162:165], v[206:209], v[68:71]
	v_mfma_f32_16x16x32_bf16 v[64:67], v[174:177], v[206:209], v[64:67]
	s_setprio 0
	s_barrier
	s_and_b32 s25, s22, 0xffff
	s_mov_b32 m0, s8
	s_mov_b32 s26, s18
	s_mov_b32 s27, s19
	s_add_u32 s16, s24, 0x4000
	ds_read_b128 v[178:181], v142 offset:16384
	ds_read_b128 v[182:185], v142 offset:17408
	ds_read_b128 v[186:189], v142 offset:18432
	ds_read_b128 v[190:193], v142 offset:19456
	ds_read_b128 v[194:197], v142 offset:20480
	ds_read_b128 v[198:201], v142 offset:21504
	ds_read_b128 v[202:205], v142 offset:22528
	ds_read_b128 v[206:209], v142 offset:23552
	buffer_load_dwordx4 v137, s[24:27], 0 offen lds
	s_mov_b32 m0, s9
	s_addc_u32 s17, s22, 0
	buffer_load_dwordx4 v139, s[24:27], 0 offen lds
	s_and_b32 s17, s17, 0xffff
	s_mov_b32 m0, s76
	s_and_b32 s29, s23, 0xffff
	buffer_load_dwordx4 v137, s[16:19], 0 offen lds
	s_mov_b32 m0, s79
	s_mov_b32 s30, s18
	buffer_load_dwordx4 v139, s[16:19], 0 offen lds
	s_mov_b32 s31, s19
	s_mov_b32 m0, s3
	s_nop 0
	buffer_load_dwordx4 v136, s[28:31], 0 offen lds
	s_mov_b32 m0, s80
	s_nop 0
	buffer_load_dwordx4 v138, s[28:31], 0 offen lds
	s_waitcnt vmcnt(8)
	s_waitcnt lgkmcnt(0)
	s_barrier
	s_setprio 1
	v_mfma_f32_16x16x32_bf16 v[60:63], v[132:135], v[178:181], v[60:63]
	v_mfma_f32_16x16x32_bf16 v[56:59], v[150:153], v[178:181], v[56:59]
	v_mfma_f32_16x16x32_bf16 v[44:47], v[132:135], v[186:189], v[44:47]
	v_mfma_f32_16x16x32_bf16 v[40:43], v[150:153], v[186:189], v[40:43]
	v_mfma_f32_16x16x32_bf16 v[28:31], v[132:135], v[194:197], v[28:31]
	v_mfma_f32_16x16x32_bf16 v[24:27], v[150:153], v[194:197], v[24:27]
	v_mfma_f32_16x16x32_bf16 v[12:15], v[132:135], v[202:205], v[12:15]
	v_mfma_f32_16x16x32_bf16 v[8:11], v[150:153], v[202:205], v[8:11]
	v_mfma_f32_16x16x32_bf16 v[60:63], v[146:149], v[182:185], v[60:63]
	v_mfma_f32_16x16x32_bf16 v[56:59], v[154:157], v[182:185], v[56:59]
	v_mfma_f32_16x16x32_bf16 v[44:47], v[146:149], v[190:193], v[44:47]
	v_mfma_f32_16x16x32_bf16 v[40:43], v[154:157], v[190:193], v[40:43]
	v_mfma_f32_16x16x32_bf16 v[28:31], v[146:149], v[198:201], v[28:31]
	v_mfma_f32_16x16x32_bf16 v[24:27], v[154:157], v[198:201], v[24:27]
	v_mfma_f32_16x16x32_bf16 v[12:15], v[146:149], v[206:209], v[12:15]
	v_mfma_f32_16x16x32_bf16 v[8:11], v[154:157], v[206:209], v[8:11]
	v_mfma_f32_16x16x32_bf16 v[52:55], v[158:161], v[178:181], v[52:55]
	v_mfma_f32_16x16x32_bf16 v[48:51], v[166:169], v[178:181], v[48:51]
	v_mfma_f32_16x16x32_bf16 v[36:39], v[158:161], v[186:189], v[36:39]
	v_mfma_f32_16x16x32_bf16 v[32:35], v[166:169], v[186:189], v[32:35]
	v_mfma_f32_16x16x32_bf16 v[20:23], v[158:161], v[194:197], v[20:23]
	v_mfma_f32_16x16x32_bf16 v[16:19], v[166:169], v[194:197], v[16:19]
	v_mfma_f32_16x16x32_bf16 v[4:7], v[158:161], v[202:205], v[4:7]
	v_mfma_f32_16x16x32_bf16 v[0:3], v[166:169], v[202:205], v[0:3]
	v_mfma_f32_16x16x32_bf16 v[52:55], v[162:165], v[182:185], v[52:55]
	v_mfma_f32_16x16x32_bf16 v[48:51], v[174:177], v[182:185], v[48:51]
	v_mfma_f32_16x16x32_bf16 v[36:39], v[162:165], v[190:193], v[36:39]
	v_mfma_f32_16x16x32_bf16 v[32:35], v[174:177], v[190:193], v[32:35]
	v_mfma_f32_16x16x32_bf16 v[20:23], v[162:165], v[198:201], v[20:23]
	v_mfma_f32_16x16x32_bf16 v[16:19], v[174:177], v[198:201], v[16:19]
	v_mfma_f32_16x16x32_bf16 v[4:7], v[162:165], v[206:209], v[4:7]
	v_mfma_f32_16x16x32_bf16 v[0:3], v[174:177], v[206:209], v[0:3]
	s_setprio 0
	s_barrier
; #define PG8_STAGE(bufoff, gbase, voff) do { const __amdgpu_buffer_rsrc_t _rs = __builtin_amdgcn_make_buffer_rsrc((void*)(gbase), 0, 0x7fffffff, 0x00020000); _Pragma("unroll") for (int _i = 0; _i < 2; ++_i) \
;         __builtin_amdgcn_raw_ptr_buffer_load_lds(_rs, (LAS unsigned*)(lds + (bufoff) + ldsw + _i * 8192), 16, (int)(voff)[_i], 0, 0, 0); } while (0)
; #define PG8_WAIT_V(n) asm volatile("s_waitcnt vmcnt(" #n ")" ::: "memory")
; #define PG8_WAIT_L(n) asm volatile("s_waitcnt lgkmcnt(" #n ")" ::: "memory")
; #define PG8_BAR __builtin_amdgcn_s_barrier()
; #define PG8_SCHED __builtin_amdgcn_sched_barrier(0)
; template <class Epi, class Sched, bool F8 = false>
; __device__ __forceinline__ void gemm_phase(LAS unsigned char* lds, const int lda, const int ldb, const Sched& S, const Epi& E) {
;     ...
;             PG8_LDB(B0, 1, 0); PG8_LDB(B1, 1, 1); PG8_SCHED; PG8_LDA(At, 1, 0); PG8_STAGE(PG8_SA(0, 1), a2 + hstepA, voffA);
;             PG8_WAIT_V(8); PG8_WAIT_L(0); PG8_BAR; PG8_MMA(0, 0, At, B0); PG8_MMA(0, 1, At, B1); PG8_BAR; PG8_SCHED;
;             PG8_LDA(At, 1, 1); PG8_STAGE(PG8_SB(1, 0), b3, voffB); PG8_STAGE(PG8_SB(1, 1), b3 + hstepB, voffB); PG8_STAGE(PG8_SA(1, 0), a3, voffA);
;             PG8_WAIT_V(8); PG8_WAIT_L(0); PG8_BAR; PG8_MMA(1, 0, At, B0); PG8_MMA(1, 1, At, B1); PG8_BAR; PG8_SCHED;
	ds_read_b128 v[132:135], v143
	ds_read_b128 v[146:149], v143 offset:1024
	ds_read_b128 v[150:153], v143 offset:2048
	ds_read_b128 v[154:157], v143 offset:3072
	ds_read_b128 v[158:161], v144
	ds_read_b128 v[162:165], v144 offset:1024
	ds_read_b128 v[166:169], v144 offset:2048
	ds_read_b128 v[174:177], v144 offset:3072
	s_add_u32 s16, s28, 0x100000
	s_addc_u32 s17, s23, 0
	s_and_b32 s17, s17, 0xffff
	s_mov_b32 m0, s81
	ds_read_b128 v[178:181], v142 offset:32768
	ds_read_b128 v[182:185], v142 offset:33792
	ds_read_b128 v[186:189], v142 offset:34816
	ds_read_b128 v[190:193], v142 offset:35840
	ds_read_b128 v[194:197], v142 offset:36864
	ds_read_b128 v[198:201], v142 offset:37888
	ds_read_b128 v[202:205], v142 offset:38912
	ds_read_b128 v[206:209], v142 offset:39936
	buffer_load_dwordx4 v136, s[16:19], 0 offen lds
	s_mov_b32 m0, s82
	s_nop 0
	buffer_load_dwordx4 v138, s[16:19], 0 offen lds
	s_waitcnt vmcnt(8)
	s_waitcnt lgkmcnt(0)
	s_barrier
	s_setprio 1
	v_mfma_f32_16x16x32_bf16 v[124:127], v[132:135], v[178:181], v[124:127]
	v_mfma_f32_16x16x32_bf16 v[120:123], v[150:153], v[178:181], v[120:123]
	v_mfma_f32_16x16x32_bf16 v[108:111], v[132:135], v[186:189], v[108:111]
	v_mfma_f32_16x16x32_bf16 v[104:107], v[150:153], v[186:189], v[104:107]
	v_mfma_f32_16x16x32_bf16 v[92:95], v[132:135], v[194:197], v[92:95]
	v_mfma_f32_16x16x32_bf16 v[88:91], v[150:153], v[194:197], v[88:91]
	v_mfma_f32_16x16x32_bf16 v[76:79], v[132:135], v[202:205], v[76:79]
	v_mfma_f32_16x16x32_bf16 v[72:75], v[150:153], v[202:205], v[72:75]
	v_mfma_f32_16x16x32_bf16 v[124:127], v[146:149], v[182:185], v[124:127]
	v_mfma_f32_16x16x32_bf16 v[120:123], v[154:157], v[182:185], v[120:123]
	v_mfma_f32_16x16x32_bf16 v[108:111], v[146:149], v[190:193], v[108:111]
	v_mfma_f32_16x16x32_bf16 v[104:107], v[154:157], v[190:193], v[104:107]
	v_mfma_f32_16x16x32_bf16 v[92:95], v[146:149], v[198:201], v[92:95]
	v_mfma_f32_16x16x32_bf16 v[88:91], v[154:157], v[198:201], v[88:91]
	v_mfma_f32_16x16x32_bf16 v[76:79], v[146:149], v[206:209], v[76:79]
	v_mfma_f32_16x16x32_bf16 v[72:75], v[154:157], v[206:209], v[72:75]
	v_mfma_f32_16x16x32_bf16 v[116:119], v[158:161], v[178:181], v[116:119]
	v_mfma_f32_16x16x32_bf16 v[112:115], v[166:169], v[178:181], v[112:115]
	v_mfma_f32_16x16x32_bf16 v[100:103], v[158:161], v[186:189], v[100:103]
	v_mfma_f32_16x16x32_bf16 v[96:99], v[166:169], v[186:189], v[96:99]
	v_mfma_f32_16x16x32_bf16 v[84:87], v[158:161], v[194:197], v[84:87]
	v_mfma_f32_16x16x32_bf16 v[80:83], v[166:169], v[194:197], v[80:83]
	v_mfma_f32_16x16x32_bf16 v[68:71], v[158:161], v[202:205], v[68:71]
	v_mfma_f32_16x16x32_bf16 v[64:67], v[166:169], v[202:205], v[64:67]
	v_mfma_f32_16x16x32_bf16 v[116:119], v[162:165], v[182:185], v[116:119]
	v_mfma_f32_16x16x32_bf16 v[112:115], v[174:177], v[182:185], v[112:115]
	v_mfma_f32_16x16x32_bf16 v[100:103], v[162:165], v[190:193], v[100:103]
	v_mfma_f32_16x16x32_bf16 v[96:99], v[174:177], v[190:193], v[96:99]
	v_mfma_f32_16x16x32_bf16 v[84:87], v[162:165], v[198:201], v[84:87]
	v_mfma_f32_16x16x32_bf16 v[80:83], v[174:177], v[198:201], v[80:83]
	v_mfma_f32_16x16x32_bf16 v[68:71], v[162:165], v[206:209], v[68:71]
	v_mfma_f32_16x16x32_bf16 v[64:67], v[174:177], v[206:209], v[64:67]
	s_setprio 0
	s_barrier
	s_add_u32 s16, s24, 0x8000
	s_addc_u32 s17, s22, 0
	s_mov_b32 m0, s87
	s_and_b32 s17, s17, 0xffff
	ds_read_b128 v[178:181], v142 offset:49152
	ds_read_b128 v[182:185], v142 offset:50176
	ds_read_b128 v[186:189], v142 offset:51200
	ds_read_b128 v[190:193], v142 offset:52224
	ds_read_b128 v[194:197], v142 offset:53248
	ds_read_b128 v[198:201], v142 offset:54272
	ds_read_b128 v[202:205], v142 offset:55296
	ds_read_b128 v[206:209], v142 offset:56320
	buffer_load_dwordx4 v137, s[16:19], 0 offen lds
	s_mov_b32 m0, s88
	s_mov_b32 s23, s19
	buffer_load_dwordx4 v139, s[16:19], 0 offen lds
	s_add_u32 s16, s24, 0xc000
	s_addc_u32 s17, s22, 0
	s_and_b32 s17, s17, 0xffff
	s_mov_b32 m0, s91
	s_and_b32 s21, s21, 0xffff
	buffer_load_dwordx4 v137, s[16:19], 0 offen lds
	s_mov_b32 m0, s92
	s_mov_b32 s22, s18
	buffer_load_dwordx4 v139, s[16:19], 0 offen lds
	s_mov_b32 m0, s89
	s_nop 0
	buffer_load_dwordx4 v136, s[20:23], 0 offen lds
	s_mov_b32 m0, s90
	s_nop 0
	buffer_load_dwordx4 v138, s[20:23], 0 offen lds
	s_waitcnt vmcnt(8)
	s_waitcnt lgkmcnt(0)
	s_barrier
	s_setprio 1
	v_mfma_f32_16x16x32_bf16 v[60:63], v[132:135], v[178:181], v[60:63]
	v_mfma_f32_16x16x32_bf16 v[56:59], v[150:153], v[178:181], v[56:59]
	v_mfma_f32_16x16x32_bf16 v[44:47], v[132:135], v[186:189], v[44:47]
	v_mfma_f32_16x16x32_bf16 v[40:43], v[150:153], v[186:189], v[40:43]
	v_mfma_f32_16x16x32_bf16 v[28:31], v[132:135], v[194:197], v[28:31]
	v_mfma_f32_16x16x32_bf16 v[24:27], v[150:153], v[194:197], v[24:27]
	v_mfma_f32_16x16x32_bf16 v[12:15], v[132:135], v[202:205], v[12:15]
	v_mfma_f32_16x16x32_bf16 v[8:11], v[150:153], v[202:205], v[8:11]
	v_mfma_f32_16x16x32_bf16 v[60:63], v[146:149], v[182:185], v[60:63]
	v_mfma_f32_16x16x32_bf16 v[56:59], v[154:157], v[182:185], v[56:59]
	v_mfma_f32_16x16x32_bf16 v[44:47], v[146:149], v[190:193], v[44:47]
	v_mfma_f32_16x16x32_bf16 v[40:43], v[154:157], v[190:193], v[40:43]
	v_mfma_f32_16x16x32_bf16 v[28:31], v[146:149], v[198:201], v[28:31]
	v_mfma_f32_16x16x32_bf16 v[24:27], v[154:157], v[198:201], v[24:27]
	v_mfma_f32_16x16x32_bf16 v[12:15], v[146:149], v[206:209], v[12:15]
	v_mfma_f32_16x16x32_bf16 v[8:11], v[154:157], v[206:209], v[8:11]
	v_mfma_f32_16x16x32_bf16 v[52:55], v[158:161], v[178:181], v[52:55]
	v_mfma_f32_16x16x32_bf16 v[48:51], v[166:169], v[178:181], v[48:51]
	v_mfma_f32_16x16x32_bf16 v[36:39], v[158:161], v[186:189], v[36:39]
	v_mfma_f32_16x16x32_bf16 v[32:35], v[166:169], v[186:189], v[32:35]
	v_mfma_f32_16x16x32_bf16 v[20:23], v[158:161], v[194:197], v[20:23]
	v_mfma_f32_16x16x32_bf16 v[16:19], v[166:169], v[194:197], v[16:19]
	v_mfma_f32_16x16x32_bf16 v[4:7], v[158:161], v[202:205], v[4:7]
	v_mfma_f32_16x16x32_bf16 v[0:3], v[166:169], v[202:205], v[0:3]
	v_mfma_f32_16x16x32_bf16 v[52:55], v[162:165], v[182:185], v[52:55]
	v_mfma_f32_16x16x32_bf16 v[48:51], v[174:177], v[182:185], v[48:51]
	v_mfma_f32_16x16x32_bf16 v[36:39], v[162:165], v[190:193], v[36:39]
	v_mfma_f32_16x16x32_bf16 v[32:35], v[174:177], v[190:193], v[32:35]
	v_mfma_f32_16x16x32_bf16 v[20:23], v[162:165], v[198:201], v[20:23]
	v_mfma_f32_16x16x32_bf16 v[16:19], v[174:177], v[198:201], v[16:19]
	v_mfma_f32_16x16x32_bf16 v[4:7], v[162:165], v[206:209], v[4:7]
	v_mfma_f32_16x16x32_bf16 v[0:3], v[174:177], v[206:209], v[0:3]
	s_setprio 0
	s_barrier
	s_add_i32 s69, s69, 2
	s_add_u32 s7, s7, 0x10000
	s_addc_u32 s62, s62, 0
	s_add_u32 s63, s63, 0x100
	s_addc_u32 s67, s67, 0
	s_cmp_gt_u32 s69, 61
	s_cbranch_scc0 .LBB0_116
	s_and_b64 vcc, exec, s[38:39]
	s_cbranch_vccz .LBB0_119
	s_barrier

; #define PG8_STAGE(bufoff, gbase, voff) do { const __amdgpu_buffer_rsrc_t _rs = __builtin_amdgcn_make_buffer_rsrc((void*)(gbase), 0, 0x7fffffff, 0x00020000); _Pragma("unroll") for (int _i = 0; _i < 2; ++_i) \
;         __builtin_amdgcn_raw_ptr_buffer_load_lds(_rs, (LAS unsigned*)(lds + (bufoff) + ldsw + _i * 8192), 16, (int)(voff)[_i], 0, 0, 0); } while (0)
; #define PG8_WAIT_V(n) asm volatile("s_waitcnt vmcnt(" #n ")" ::: "memory")
; #define PG8_WAIT_L(n) asm volatile("s_waitcnt lgkmcnt(" #n ")" ::: "memory")
; #define PG8_BAR __builtin_amdgcn_s_barrier()
; #define PG8_SCHED __builtin_amdgcn_sched_barrier(0)
; template <class Epi, class Sched, bool F8 = false>
; __device__ __forceinline__ void gemm_phase(LAS unsigned char* lds, const int lda, const int ldb, const Sched& S, const Epi& E) {
;     ...
;             const bool last = (t == nt - 2);
;             const char* a1 = cA + (size_t)(t + 1) * kstep;
;             const char* a2 = last ? nA : cA + (size_t)(t + 2) * kstep; const char* b2 = last ? nB : cB + (size_t)(t + 2) * kstepB;
;             const char* a3 = a2 + kstep; const char* b3 = b2 + kstepB;
;     ...
;             PG8_LDB(B0, 0, 0); PG8_LDB(B1, 0, 1); PG8_SCHED; PG8_LDA(At, 0, 0); PG8_STAGE(PG8_SA(1, 1), a1 + hstepA, voffA);
;             PG8_WAIT_V(8); PG8_WAIT_L(0); PG8_BAR; PG8_MMA(0, 0, At, B0); PG8_MMA(0, 1, At, B1); PG8_BAR; PG8_SCHED;
;             PG8_LDA(At, 0, 1); PG8_STAGE(PG8_SB(0, 0), b2, voffB); PG8_STAGE(PG8_SB(0, 1), b2 + hstepB, voffB); PG8_STAGE(PG8_SA(0, 0), a2, voffA);
;             PG8_WAIT_V(8); PG8_WAIT_L(0); PG8_BAR; PG8_MMA(1, 0, At, B0); PG8_MMA(1, 1, At, B1); PG8_BAR; PG8_SCHED;
.LBB0_174:
	ds_read_b128 v[146:149], v140
	ds_read_b128 v[150:153], v140 offset:1024
	ds_read_b128 v[154:157], v140 offset:2048
	ds_read_b128 v[158:161], v140 offset:3072
	ds_read_b128 v[162:165], v141
	ds_read_b128 v[166:169], v141 offset:1024
	ds_read_b128 v[174:177], v141 offset:2048
	ds_read_b128 v[178:181], v141 offset:3072
	s_add_u32 s16, s63, 0xfff80080
	s_addc_u32 s17, s67, -1
	s_cmp_eq_u32 s69, 28
	s_cselect_b32 s28, s70, s16
	s_cselect_b32 s23, s71, s17
	s_cselect_b32 s22, s73, s62
	s_cselect_b32 s24, s72, s7
	s_add_u32 s20, s28, 0x80
	s_addc_u32 s21, s23, 0
	s_and_b32 s17, s67, 0xffff
	s_mov_b32 s16, s63
	s_mov_b32 m0, s96
	ds_read_b128 v[182:185], v142
	ds_read_b128 v[186:189], v142 offset:1024
	ds_read_b128 v[190:193], v142 offset:2048
	ds_read_b128 v[194:197], v142 offset:3072
	ds_read_b128 v[198:201], v142 offset:4096
	ds_read_b128 v[202:205], v142 offset:5120
	ds_read_b128 v[206:209], v142 offset:6144
	ds_read_b128 v[210:213], v142 offset:7168
	buffer_load_dwordx4 v136, s[16:19], 0 offen lds
	s_mov_b32 m0, s97
	s_nop 0
	buffer_load_dwordx4 v138, s[16:19], 0 offen lds
	s_waitcnt vmcnt(8)
	s_waitcnt lgkmcnt(0)
	s_barrier
	s_setprio 1
	v_mfma_scale_f32_16x16x128_f8f6f4 v[124:127], v[146:153], v[182:189], v[124:127], v143, v143 op_sel_hi:[0,0,0]
	v_mfma_scale_f32_16x16x128_f8f6f4 v[120:123], v[154:161], v[182:189], v[120:123], v143, v143 op_sel_hi:[0,0,0]
	v_mfma_scale_f32_16x16x128_f8f6f4 v[108:111], v[146:153], v[190:197], v[108:111], v143, v143 op_sel_hi:[0,0,0]
	v_mfma_scale_f32_16x16x128_f8f6f4 v[104:107], v[154:161], v[190:197], v[104:107], v143, v143 op_sel_hi:[0,0,0]
	v_mfma_scale_f32_16x16x128_f8f6f4 v[132:135], v[146:153], v[198:205], v[92:95], v143, v143 op_sel_hi:[0,0,0]
	v_mfma_scale_f32_16x16x128_f8f6f4 v[214:217], v[154:161], v[198:205], v[88:91], v143, v143 op_sel_hi:[0,0,0]
	v_mfma_scale_f32_16x16x128_f8f6f4 v[218:221], v[146:153], v[206:213], v[76:79], v143, v143 op_sel_hi:[0,0,0]
	v_mfma_scale_f32_16x16x128_f8f6f4 v[222:225], v[154:161], v[206:213], v[72:75], v143, v143 op_sel_hi:[0,0,0]
	v_mfma_scale_f32_16x16x128_f8f6f4 v[116:119], v[162:169], v[182:189], v[116:119], v143, v143 op_sel_hi:[0,0,0]
	v_mfma_scale_f32_16x16x128_f8f6f4 v[112:115], v[174:181], v[182:189], v[112:115], v143, v143 op_sel_hi:[0,0,0]
	v_mfma_scale_f32_16x16x128_f8f6f4 v[100:103], v[162:169], v[190:197], v[100:103], v143, v143 op_sel_hi:[0,0,0]
	v_mfma_scale_f32_16x16x128_f8f6f4 v[96:99], v[174:181], v[190:197], v[96:99], v143, v143 op_sel_hi:[0,0,0]
	v_mfma_scale_f32_16x16x128_f8f6f4 v[182:185], v[162:169], v[198:205], v[84:87], v143, v143 op_sel_hi:[0,0,0]
	v_mfma_scale_f32_16x16x128_f8f6f4 v[186:189], v[174:181], v[198:205], v[80:83], v143, v143 op_sel_hi:[0,0,0]
	v_mfma_scale_f32_16x16x128_f8f6f4 v[190:193], v[162:169], v[206:213], v[68:71], v143, v143 op_sel_hi:[0,0,0]
	v_mfma_scale_f32_16x16x128_f8f6f4 v[194:197], v[174:181], v[206:213], v[64:67], v143, v143 op_sel_hi:[0,0,0]
	s_setprio 0
	s_barrier
	s_and_b32 s25, s22, 0xffff
	s_mov_b32 m0, s79
	s_mov_b32 s26, s18
	s_mov_b32 s27, s19
	s_add_u32 s16, s24, 0x4000
	ds_read_b128 v[64:67], v142 offset:16384
	ds_read_b128 v[68:71], v142 offset:17408
	ds_read_b128 v[72:75], v142 offset:18432
	ds_read_b128 v[76:79], v142 offset:19456
	ds_read_b128 v[80:83], v142 offset:20480
	ds_read_b128 v[84:87], v142 offset:21504
	ds_read_b128 v[88:91], v142 offset:22528
	ds_read_b128 v[92:95], v142 offset:23552
	buffer_load_dwordx4 v137, s[24:27], 0 offen lds
	s_mov_b32 m0, s80
	s_addc_u32 s17, s22, 0
	buffer_load_dwordx4 v139, s[24:27], 0 offen lds
	s_and_b32 s17, s17, 0xffff
	s_mov_b32 m0, s81
	s_and_b32 s29, s23, 0xffff
	buffer_load_dwordx4 v137, s[16:19], 0 offen lds
	s_mov_b32 m0, s82
	s_mov_b32 s30, s18
	buffer_load_dwordx4 v139, s[16:19], 0 offen lds
	s_mov_b32 s31, s19
	s_mov_b32 m0, s76
	s_nop 0
	buffer_load_dwordx4 v136, s[28:31], 0 offen lds
	s_mov_b32 m0, s83
	s_nop 0
	buffer_load_dwordx4 v138, s[28:31], 0 offen lds
	s_waitcnt vmcnt(8)
	s_waitcnt lgkmcnt(0)
	s_barrier
	s_setprio 1
	v_mfma_scale_f32_16x16x128_f8f6f4 v[60:63], v[146:153], v[64:71], v[60:63], v143, v143 op_sel_hi:[0,0,0]
	v_mfma_scale_f32_16x16x128_f8f6f4 v[56:59], v[154:161], v[64:71], v[56:59], v143, v143 op_sel_hi:[0,0,0]
	v_mfma_scale_f32_16x16x128_f8f6f4 v[198:201], v[146:153], v[72:79], v[44:47], v143, v143 op_sel_hi:[0,0,0]
	v_mfma_scale_f32_16x16x128_f8f6f4 v[202:205], v[154:161], v[72:79], v[40:43], v143, v143 op_sel_hi:[0,0,0]
	v_mfma_scale_f32_16x16x128_f8f6f4 v[206:209], v[146:153], v[80:87], v[28:31], v143, v143 op_sel_hi:[0,0,0]
	v_mfma_scale_f32_16x16x128_f8f6f4 v[210:213], v[154:161], v[80:87], v[24:27], v143, v143 op_sel_hi:[0,0,0]
	v_mfma_scale_f32_16x16x128_f8f6f4 v[226:229], v[146:153], v[88:95], v[12:15], v143, v143 op_sel_hi:[0,0,0]
	v_mfma_scale_f32_16x16x128_f8f6f4 v[230:233], v[154:161], v[88:95], v[8:11], v143, v143 op_sel_hi:[0,0,0]
	v_mfma_scale_f32_16x16x128_f8f6f4 v[52:55], v[162:169], v[64:71], v[52:55], v143, v143 op_sel_hi:[0,0,0]
	v_mfma_scale_f32_16x16x128_f8f6f4 v[48:51], v[174:181], v[64:71], v[48:51], v143, v143 op_sel_hi:[0,0,0]
	v_mfma_scale_f32_16x16x128_f8f6f4 v[234:237], v[162:169], v[72:79], v[36:39], v143, v143 op_sel_hi:[0,0,0]
	v_mfma_scale_f32_16x16x128_f8f6f4 v[238:241], v[174:181], v[72:79], v[32:35], v143, v143 op_sel_hi:[0,0,0]
	v_mfma_scale_f32_16x16x128_f8f6f4 v[242:245], v[162:169], v[80:87], v[20:23], v143, v143 op_sel_hi:[0,0,0]
	v_mfma_scale_f32_16x16x128_f8f6f4 v[246:249], v[174:181], v[80:87], v[16:19], v143, v143 op_sel_hi:[0,0,0]
	v_mfma_scale_f32_16x16x128_f8f6f4 v[250:253], v[162:169], v[88:95], v[4:7], v143, v143 op_sel_hi:[0,0,0]
	v_mfma_scale_f32_16x16x128_f8f6f4 v[170:173], v[174:181], v[88:95], v[0:3], v143, v143 op_sel_hi:[0,0,0]
	s_setprio 0
	s_barrier
; #define PG8_STAGE(bufoff, gbase, voff) do { const __amdgpu_buffer_rsrc_t _rs = __builtin_amdgcn_make_buffer_rsrc((void*)(gbase), 0, 0x7fffffff, 0x00020000); _Pragma("unroll") for (int _i = 0; _i < 2; ++_i) \
;         __builtin_amdgcn_raw_ptr_buffer_load_lds(_rs, (LAS unsigned*)(lds + (bufoff) + ldsw + _i * 8192), 16, (int)(voff)[_i], 0, 0, 0); } while (0)
; #define PG8_WAIT_V(n) asm volatile("s_waitcnt vmcnt(" #n ")" ::: "memory")
; #define PG8_WAIT_L(n) asm volatile("s_waitcnt lgkmcnt(" #n ")" ::: "memory")
; #define PG8_BAR __builtin_amdgcn_s_barrier()
; #define PG8_SCHED __builtin_amdgcn_sched_barrier(0)
; template <class Epi, class Sched, bool F8 = false>
; __device__ __forceinline__ void gemm_phase(LAS unsigned char* lds, const int lda, const int ldb, const Sched& S, const Epi& E) {
;     ...
;             PG8_LDB(B0, 1, 0); PG8_LDB(B1, 1, 1); PG8_SCHED; PG8_LDA(At, 1, 0); PG8_STAGE(PG8_SA(0, 1), a2 + hstepA, voffA);
;             PG8_WAIT_V(8); PG8_WAIT_L(0); PG8_BAR; PG8_MMA(0, 0, At, B0); PG8_MMA(0, 1, At, B1); PG8_BAR; PG8_SCHED;
;             PG8_LDA(At, 1, 1); PG8_STAGE(PG8_SB(1, 0), b3, voffB); PG8_STAGE(PG8_SB(1, 1), b3 + hstepB, voffB); PG8_STAGE(PG8_SA(1, 0), a3, voffA);
;             PG8_WAIT_V(8); PG8_WAIT_L(0); PG8_BAR; PG8_MMA(1, 0, At, B0); PG8_MMA(1, 1, At, B1); PG8_BAR; PG8_SCHED;
	s_nop 4
	ds_read_b128 v[0:3], v144
	ds_read_b128 v[4:7], v144 offset:1024
	ds_read_b128 v[16:19], v144 offset:2048
	ds_read_b128 v[20:23], v144 offset:3072
	ds_read_b128 v[146:149], v145
	ds_read_b128 v[150:153], v145 offset:1024
	ds_read_b128 v[154:157], v145 offset:2048
	ds_read_b128 v[158:161], v145 offset:3072
	s_add_u32 s16, s28, 0x80000
	s_addc_u32 s17, s23, 0
	s_and_b32 s17, s17, 0xffff
	s_mov_b32 m0, s84
	ds_read_b128 v[8:11], v142 offset:32768
	ds_read_b128 v[12:15], v142 offset:33792
	ds_read_b128 v[24:27], v142 offset:34816
	ds_read_b128 v[28:31], v142 offset:35840
	ds_read_b128 v[32:35], v142 offset:36864
	ds_read_b128 v[36:39], v142 offset:37888
	ds_read_b128 v[40:43], v142 offset:38912
	ds_read_b128 v[44:47], v142 offset:39936
	buffer_load_dwordx4 v136, s[16:19], 0 offen lds
	s_mov_b32 m0, s85
	s_nop 0
	buffer_load_dwordx4 v138, s[16:19], 0 offen lds
	s_waitcnt vmcnt(8)
	s_waitcnt lgkmcnt(0)
	s_barrier
	s_setprio 1
	v_mfma_scale_f32_16x16x128_f8f6f4 v[124:127], v[0:7], v[8:15], v[124:127], v143, v143 op_sel_hi:[0,0,0]
	v_mfma_scale_f32_16x16x128_f8f6f4 v[120:123], v[16:23], v[8:15], v[120:123], v143, v143 op_sel_hi:[0,0,0]
	v_mfma_scale_f32_16x16x128_f8f6f4 v[108:111], v[0:7], v[24:31], v[108:111], v143, v143 op_sel_hi:[0,0,0]
	v_mfma_scale_f32_16x16x128_f8f6f4 v[104:107], v[16:23], v[24:31], v[104:107], v143, v143 op_sel_hi:[0,0,0]
	v_mfma_scale_f32_16x16x128_f8f6f4 v[92:95], v[0:7], v[32:39], v[132:135], v143, v143 op_sel_hi:[0,0,0]
	v_mfma_scale_f32_16x16x128_f8f6f4 v[88:91], v[16:23], v[32:39], v[214:217], v143, v143 op_sel_hi:[0,0,0]
	v_mfma_scale_f32_16x16x128_f8f6f4 v[76:79], v[0:7], v[40:47], v[218:221], v143, v143 op_sel_hi:[0,0,0]
	v_mfma_scale_f32_16x16x128_f8f6f4 v[72:75], v[16:23], v[40:47], v[222:225], v143, v143 op_sel_hi:[0,0,0]
	v_mfma_scale_f32_16x16x128_f8f6f4 v[116:119], v[146:153], v[8:15], v[116:119], v143, v143 op_sel_hi:[0,0,0]
	v_mfma_scale_f32_16x16x128_f8f6f4 v[112:115], v[154:161], v[8:15], v[112:115], v143, v143 op_sel_hi:[0,0,0]
	v_mfma_scale_f32_16x16x128_f8f6f4 v[100:103], v[146:153], v[24:31], v[100:103], v143, v143 op_sel_hi:[0,0,0]
	v_mfma_scale_f32_16x16x128_f8f6f4 v[96:99], v[154:161], v[24:31], v[96:99], v143, v143 op_sel_hi:[0,0,0]
	v_mfma_scale_f32_16x16x128_f8f6f4 v[84:87], v[146:153], v[32:39], v[182:185], v143, v143 op_sel_hi:[0,0,0]
	v_mfma_scale_f32_16x16x128_f8f6f4 v[80:83], v[154:161], v[32:39], v[186:189], v143, v143 op_sel_hi:[0,0,0]
	v_mfma_scale_f32_16x16x128_f8f6f4 v[68:71], v[146:153], v[40:47], v[190:193], v143, v143 op_sel_hi:[0,0,0]
	v_mfma_scale_f32_16x16x128_f8f6f4 v[64:67], v[154:161], v[40:47], v[194:197], v143, v143 op_sel_hi:[0,0,0]
	s_setprio 0
	s_barrier
	s_add_u32 s16, s24, 0x8000
	s_addc_u32 s17, s22, 0
	s_mov_b32 m0, s90
	s_and_b32 s17, s17, 0xffff
	ds_read_b128 v[32:35], v142 offset:49152
	ds_read_b128 v[36:39], v142 offset:50176
	ds_read_b128 v[162:165], v142 offset:51200
	ds_read_b128 v[166:169], v142 offset:52224
	ds_read_b128 v[174:177], v142 offset:53248
	ds_read_b128 v[178:181], v142 offset:54272
	ds_read_b128 v[182:185], v142 offset:55296
	ds_read_b128 v[186:189], v142 offset:56320
	buffer_load_dwordx4 v137, s[16:19], 0 offen lds
	s_mov_b32 m0, s91
	s_mov_b32 s23, s19
	buffer_load_dwordx4 v139, s[16:19], 0 offen lds
	s_add_u32 s16, s24, 0xc000
	s_addc_u32 s17, s22, 0
	s_and_b32 s17, s17, 0xffff
	s_mov_b32 m0, s94
	s_and_b32 s21, s21, 0xffff
	buffer_load_dwordx4 v137, s[16:19], 0 offen lds
	s_mov_b32 m0, s95
	s_mov_b32 s22, s18
	buffer_load_dwordx4 v139, s[16:19], 0 offen lds
	s_mov_b32 m0, s92
	s_nop 0
	buffer_load_dwordx4 v136, s[20:23], 0 offen lds
	s_mov_b32 m0, s93
	s_nop 0
	buffer_load_dwordx4 v138, s[20:23], 0 offen lds
	s_waitcnt vmcnt(8)
	s_waitcnt lgkmcnt(0)
	s_barrier
	s_setprio 1
	v_mfma_scale_f32_16x16x128_f8f6f4 v[60:63], v[0:7], v[32:39], v[60:63], v143, v143 op_sel_hi:[0,0,0]
	v_mfma_scale_f32_16x16x128_f8f6f4 v[56:59], v[16:23], v[32:39], v[56:59], v143, v143 op_sel_hi:[0,0,0]
	v_mfma_scale_f32_16x16x128_f8f6f4 v[44:47], v[0:7], v[162:169], v[198:201], v143, v143 op_sel_hi:[0,0,0]
	v_mfma_scale_f32_16x16x128_f8f6f4 v[40:43], v[16:23], v[162:169], v[202:205], v143, v143 op_sel_hi:[0,0,0]
	v_mfma_scale_f32_16x16x128_f8f6f4 v[28:31], v[0:7], v[174:181], v[206:209], v143, v143 op_sel_hi:[0,0,0]
	v_mfma_scale_f32_16x16x128_f8f6f4 v[24:27], v[16:23], v[174:181], v[210:213], v143, v143 op_sel_hi:[0,0,0]
	v_mfma_scale_f32_16x16x128_f8f6f4 v[12:15], v[0:7], v[182:189], v[226:229], v143, v143 op_sel_hi:[0,0,0]
	v_mfma_scale_f32_16x16x128_f8f6f4 v[8:11], v[16:23], v[182:189], v[230:233], v143, v143 op_sel_hi:[0,0,0]
	v_mfma_scale_f32_16x16x128_f8f6f4 v[52:55], v[146:153], v[32:39], v[52:55], v143, v143 op_sel_hi:[0,0,0]
	v_mfma_scale_f32_16x16x128_f8f6f4 v[48:51], v[154:161], v[32:39], v[48:51], v143, v143 op_sel_hi:[0,0,0]
	v_mfma_scale_f32_16x16x128_f8f6f4 v[36:39], v[146:153], v[162:169], v[234:237], v143, v143 op_sel_hi:[0,0,0]
	v_mfma_scale_f32_16x16x128_f8f6f4 v[32:35], v[154:161], v[162:169], v[238:241], v143, v143 op_sel_hi:[0,0,0]
	v_mfma_scale_f32_16x16x128_f8f6f4 v[20:23], v[146:153], v[174:181], v[242:245], v143, v143 op_sel_hi:[0,0,0]
	v_mfma_scale_f32_16x16x128_f8f6f4 v[16:19], v[154:161], v[174:181], v[246:249], v143, v143 op_sel_hi:[0,0,0]
	v_mfma_scale_f32_16x16x128_f8f6f4 v[4:7], v[146:153], v[182:189], v[250:253], v143, v143 op_sel_hi:[0,0,0]
	v_mfma_scale_f32_16x16x128_f8f6f4 v[0:3], v[154:161], v[182:189], v[170:173], v143, v143 op_sel_hi:[0,0,0]
	s_setprio 0
	s_barrier
	s_add_i32 s69, s69, 2
	s_add_u32 s7, s7, 0x10000
	s_addc_u32 s62, s62, 0
	s_add_u32 s63, s63, 0x100
	s_addc_u32 s67, s67, 0
	s_cmp_gt_u32 s69, 29
	s_cbranch_scc0 .LBB0_174
	s_and_b64 vcc, exec, s[38:39]
	s_cbranch_vccz .LBB0_177
	s_barrier

; #define PG8_STAGE(bufoff, gbase, voff) do { const __amdgpu_buffer_rsrc_t _rs = __builtin_amdgcn_make_buffer_rsrc((void*)(gbase), 0, 0x7fffffff, 0x00020000); _Pragma("unroll") for (int _i = 0; _i < 2; ++_i) \
;         __builtin_amdgcn_raw_ptr_buffer_load_lds(_rs, (LAS unsigned*)(lds + (bufoff) + ldsw + _i * 8192), 16, (int)(voff)[_i], 0, 0, 0); } while (0)
; #define PG8_WAIT_V(n) asm volatile("s_waitcnt vmcnt(" #n ")" ::: "memory")
; #define PG8_WAIT_L(n) asm volatile("s_waitcnt lgkmcnt(" #n ")" ::: "memory")
; #define PG8_BAR __builtin_amdgcn_s_barrier()
; #define PG8_SCHED __builtin_amdgcn_sched_barrier(0)
; template <class Epi, class Sched, bool F8 = false>
; __device__ __forceinline__ void gemm_phase(LAS unsigned char* lds, const int lda, const int ldb, const Sched& S, const Epi& E) {
;     ...
;             PG8_LDB(B0, 0, 0); PG8_LDB(B1, 0, 1); PG8_SCHED; PG8_LDA(At, 0, 0); PG8_STAGE(PG8_SA(1, 1), a1 + hstepA, voffA);
;             PG8_WAIT_V(8); PG8_WAIT_L(0); PG8_BAR; PG8_MMA(0, 0, At, B0); PG8_MMA(0, 1, At, B1); PG8_BAR; PG8_SCHED;
;             PG8_LDA(At, 0, 1); PG8_STAGE(PG8_SB(0, 0), b2, voffB); PG8_STAGE(PG8_SB(0, 1), b2 + hstepB, voffB); PG8_STAGE(PG8_SA(0, 0), a2, voffA);
;             PG8_WAIT_V(8); PG8_WAIT_L(0); PG8_BAR; PG8_MMA(1, 0, At, B0); PG8_MMA(1, 1, At, B1); PG8_BAR; PG8_SCHED;
.LBB0_408:
	ds_read_b128 v[104:107], v180
	ds_read_b128 v[108:111], v180 offset:1024
	ds_read_b128 v[136:139], v180 offset:2048
	ds_read_b128 v[140:143], v180 offset:3072
	ds_read_b128 v[148:151], v181
	ds_read_b128 v[152:155], v181 offset:1024
	ds_read_b128 v[156:159], v181 offset:2048
	ds_read_b128 v[160:163], v181 offset:3072
	s_add_i32 s64, s4, 2
	s_add_u32 s5, vcc_hi, 0xfff80080
	s_addc_u32 s16, s35, -1
	s_cmp_eq_u32 s62, s4
	s_cselect_b32 s40, s70, s5
	s_cselect_b32 s19, s71, s16
	s_cselect_b32 s18, s73, vcc_lo
	s_cselect_b32 s36, s72, s63
	s_add_u32 s16, s40, 0x80
	s_addc_u32 s17, s19, 0
	s_and_b32 s5, s35, 0xffff
	s_mov_b32 s4, vcc_hi
	s_mov_b32 m0, s92
	ds_read_b128 v[164:167], v182
	ds_read_b128 v[168:171], v182 offset:1024
	ds_read_b128 v[172:175], v182 offset:2048
	ds_read_b128 v[186:189], v182 offset:3072
	ds_read_b128 v[190:193], v182 offset:4096
	ds_read_b128 v[194:197], v182 offset:5120
	ds_read_b128 v[198:201], v182 offset:6144
	ds_read_b128 v[202:205], v182 offset:7168
	buffer_load_dwordx4 v176, s[4:7], 0 offen lds
	s_mov_b32 m0, s93
	s_nop 0
	buffer_load_dwordx4 v178, s[4:7], 0 offen lds
	s_waitcnt vmcnt(8)
	s_waitcnt lgkmcnt(0)
	s_barrier
	s_setprio 1
	v_mfma_f32_16x16x32_bf16 v[132:135], v[104:107], v[164:167], v[132:135]
	v_mfma_f32_16x16x32_bf16 v[128:131], v[136:139], v[164:167], v[128:131]
	v_mfma_f32_16x16x32_bf16 v[124:127], v[104:107], v[172:175], v[124:127]
	v_mfma_f32_16x16x32_bf16 v[120:123], v[136:139], v[172:175], v[120:123]
	v_mfma_f32_16x16x32_bf16 v[116:119], v[104:107], v[190:193], v[116:119]
	v_mfma_f32_16x16x32_bf16 v[112:115], v[136:139], v[190:193], v[112:115]
	v_mfma_f32_16x16x32_bf16 v[100:103], v[104:107], v[198:201], v[100:103]
	v_mfma_f32_16x16x32_bf16 v[96:99], v[136:139], v[198:201], v[96:99]
	v_mfma_f32_16x16x32_bf16 v[132:135], v[108:111], v[168:171], v[132:135]
	v_mfma_f32_16x16x32_bf16 v[128:131], v[140:143], v[168:171], v[128:131]
	v_mfma_f32_16x16x32_bf16 v[124:127], v[108:111], v[186:189], v[124:127]
	v_mfma_f32_16x16x32_bf16 v[120:123], v[140:143], v[186:189], v[120:123]
	v_mfma_f32_16x16x32_bf16 v[116:119], v[108:111], v[194:197], v[116:119]
	v_mfma_f32_16x16x32_bf16 v[112:115], v[140:143], v[194:197], v[112:115]
	v_mfma_f32_16x16x32_bf16 v[100:103], v[108:111], v[202:205], v[100:103]
	v_mfma_f32_16x16x32_bf16 v[96:99], v[140:143], v[202:205], v[96:99]
	v_mfma_f32_16x16x32_bf16 v[60:63], v[148:151], v[164:167], v[60:63]
	v_mfma_f32_16x16x32_bf16 v[56:59], v[156:159], v[164:167], v[56:59]
	v_mfma_f32_16x16x32_bf16 v[52:55], v[148:151], v[172:175], v[52:55]
	v_mfma_f32_16x16x32_bf16 v[48:51], v[156:159], v[172:175], v[48:51]
	v_mfma_f32_16x16x32_bf16 v[44:47], v[148:151], v[190:193], v[44:47]
	v_mfma_f32_16x16x32_bf16 v[40:43], v[156:159], v[190:193], v[40:43]
	v_mfma_f32_16x16x32_bf16 v[36:39], v[148:151], v[198:201], v[36:39]
	v_mfma_f32_16x16x32_bf16 v[32:35], v[156:159], v[198:201], v[32:35]
	v_mfma_f32_16x16x32_bf16 v[60:63], v[152:155], v[168:171], v[60:63]
	v_mfma_f32_16x16x32_bf16 v[56:59], v[160:163], v[168:171], v[56:59]
	v_mfma_f32_16x16x32_bf16 v[52:55], v[152:155], v[186:189], v[52:55]
	v_mfma_f32_16x16x32_bf16 v[48:51], v[160:163], v[186:189], v[48:51]
	v_mfma_f32_16x16x32_bf16 v[44:47], v[152:155], v[194:197], v[44:47]
	v_mfma_f32_16x16x32_bf16 v[40:43], v[160:163], v[194:197], v[40:43]
	v_mfma_f32_16x16x32_bf16 v[36:39], v[152:155], v[202:205], v[36:39]
	v_mfma_f32_16x16x32_bf16 v[32:35], v[160:163], v[202:205], v[32:35]
	s_setprio 0
	s_barrier
	s_and_b32 s37, s18, 0xffff
	s_mov_b32 m0, s75
	s_mov_b32 s38, s6
	s_mov_b32 s39, s7
	s_add_u32 s4, s36, 0x4000
	ds_read_b128 v[164:167], v182 offset:16384
	ds_read_b128 v[168:171], v182 offset:17408
	ds_read_b128 v[172:175], v182 offset:18432
	ds_read_b128 v[186:189], v182 offset:19456
	ds_read_b128 v[190:193], v182 offset:20480
	ds_read_b128 v[194:197], v182 offset:21504
	ds_read_b128 v[198:201], v182 offset:22528
	ds_read_b128 v[202:205], v182 offset:23552
	buffer_load_dwordx4 v177, s[36:39], 0 offen lds
	s_mov_b32 m0, s77
	s_addc_u32 s5, s18, 0
	buffer_load_dwordx4 v179, s[36:39], 0 offen lds
	s_and_b32 s5, s5, 0xffff
	s_mov_b32 m0, s78
	s_and_b32 s41, s19, 0xffff
	buffer_load_dwordx4 v177, s[4:7], 0 offen lds
	s_mov_b32 m0, s79
	s_mov_b32 s42, s6
	buffer_load_dwordx4 v179, s[4:7], 0 offen lds
	s_mov_b32 s43, s7
	s_mov_b32 m0, s74
	s_nop 0
	buffer_load_dwordx4 v176, s[40:43], 0 offen lds
	s_mov_b32 m0, s80
	s_nop 0
	buffer_load_dwordx4 v178, s[40:43], 0 offen lds
	s_waitcnt vmcnt(8)
	s_waitcnt lgkmcnt(0)
	s_barrier
	s_setprio 1
	v_mfma_f32_16x16x32_bf16 v[92:95], v[104:107], v[164:167], v[92:95]
	v_mfma_f32_16x16x32_bf16 v[88:91], v[136:139], v[164:167], v[88:91]
	v_mfma_f32_16x16x32_bf16 v[84:87], v[104:107], v[172:175], v[84:87]
	v_mfma_f32_16x16x32_bf16 v[80:83], v[136:139], v[172:175], v[80:83]
	v_mfma_f32_16x16x32_bf16 v[76:79], v[104:107], v[190:193], v[76:79]
	v_mfma_f32_16x16x32_bf16 v[72:75], v[136:139], v[190:193], v[72:75]
	v_mfma_f32_16x16x32_bf16 v[68:71], v[104:107], v[198:201], v[68:71]
	v_mfma_f32_16x16x32_bf16 v[64:67], v[136:139], v[198:201], v[64:67]
	v_mfma_f32_16x16x32_bf16 v[92:95], v[108:111], v[168:171], v[92:95]
	v_mfma_f32_16x16x32_bf16 v[88:91], v[140:143], v[168:171], v[88:91]
	v_mfma_f32_16x16x32_bf16 v[84:87], v[108:111], v[186:189], v[84:87]
	v_mfma_f32_16x16x32_bf16 v[80:83], v[140:143], v[186:189], v[80:83]
	v_mfma_f32_16x16x32_bf16 v[76:79], v[108:111], v[194:197], v[76:79]
	v_mfma_f32_16x16x32_bf16 v[72:75], v[140:143], v[194:197], v[72:75]
	v_mfma_f32_16x16x32_bf16 v[68:71], v[108:111], v[202:205], v[68:71]
	v_mfma_f32_16x16x32_bf16 v[64:67], v[140:143], v[202:205], v[64:67]
	v_mfma_f32_16x16x32_bf16 v[28:31], v[148:151], v[164:167], v[28:31]
	v_mfma_f32_16x16x32_bf16 v[24:27], v[156:159], v[164:167], v[24:27]
	v_mfma_f32_16x16x32_bf16 v[20:23], v[148:151], v[172:175], v[20:23]
	v_mfma_f32_16x16x32_bf16 v[16:19], v[156:159], v[172:175], v[16:19]
	v_mfma_f32_16x16x32_bf16 v[12:15], v[148:151], v[190:193], v[12:15]
	v_mfma_f32_16x16x32_bf16 v[8:11], v[156:159], v[190:193], v[8:11]
	v_mfma_f32_16x16x32_bf16 v[4:7], v[148:151], v[198:201], v[4:7]
	v_mfma_f32_16x16x32_bf16 v[0:3], v[156:159], v[198:201], v[0:3]
	v_mfma_f32_16x16x32_bf16 v[28:31], v[152:155], v[168:171], v[28:31]
	v_mfma_f32_16x16x32_bf16 v[24:27], v[160:163], v[168:171], v[24:27]
	v_mfma_f32_16x16x32_bf16 v[20:23], v[152:155], v[186:189], v[20:23]
	v_mfma_f32_16x16x32_bf16 v[16:19], v[160:163], v[186:189], v[16:19]
	v_mfma_f32_16x16x32_bf16 v[12:15], v[152:155], v[194:197], v[12:15]
	v_mfma_f32_16x16x32_bf16 v[8:11], v[160:163], v[194:197], v[8:11]
	v_mfma_f32_16x16x32_bf16 v[4:7], v[152:155], v[202:205], v[4:7]
	v_mfma_f32_16x16x32_bf16 v[0:3], v[160:163], v[202:205], v[0:3]
	s_setprio 0
	s_barrier
; #define PG8_STAGE(bufoff, gbase, voff) do { const __amdgpu_buffer_rsrc_t _rs = __builtin_amdgcn_make_buffer_rsrc((void*)(gbase), 0, 0x7fffffff, 0x00020000); _Pragma("unroll") for (int _i = 0; _i < 2; ++_i) \
;         __builtin_amdgcn_raw_ptr_buffer_load_lds(_rs, (LAS unsigned*)(lds + (bufoff) + ldsw + _i * 8192), 16, (int)(voff)[_i], 0, 0, 0); } while (0)
; #define PG8_WAIT_V(n) asm volatile("s_waitcnt vmcnt(" #n ")" ::: "memory")
; #define PG8_WAIT_L(n) asm volatile("s_waitcnt lgkmcnt(" #n ")" ::: "memory")
; #define PG8_BAR __builtin_amdgcn_s_barrier()
; #define PG8_SCHED __builtin_amdgcn_sched_barrier(0)
; template <class Epi, class Sched, bool F8 = false>
; __device__ __forceinline__ void gemm_phase(LAS unsigned char* lds, const int lda, const int ldb, const Sched& S, const Epi& E) {
;     ...
;             PG8_LDB(B0, 1, 0); PG8_LDB(B1, 1, 1); PG8_SCHED; PG8_LDA(At, 1, 0); PG8_STAGE(PG8_SA(0, 1), a2 + hstepA, voffA);
;             PG8_WAIT_V(8); PG8_WAIT_L(0); PG8_BAR; PG8_MMA(0, 0, At, B0); PG8_MMA(0, 1, At, B1); PG8_BAR; PG8_SCHED;
;             PG8_LDA(At, 1, 1); PG8_STAGE(PG8_SB(1, 0), b3, voffB); PG8_STAGE(PG8_SB(1, 1), b3 + hstepB, voffB); PG8_STAGE(PG8_SA(1, 0), a3, voffA);
;             PG8_WAIT_V(8); PG8_WAIT_L(0); PG8_BAR; PG8_MMA(1, 0, At, B0); PG8_MMA(1, 1, At, B1); PG8_BAR; PG8_SCHED;
	ds_read_b128 v[104:107], v183
	ds_read_b128 v[108:111], v183 offset:1024
	ds_read_b128 v[136:139], v183 offset:2048
	ds_read_b128 v[140:143], v183 offset:3072
	ds_read_b128 v[148:151], v184
	ds_read_b128 v[152:155], v184 offset:1024
	ds_read_b128 v[156:159], v184 offset:2048
	ds_read_b128 v[160:163], v184 offset:3072
	s_add_u32 s4, s40, 0x80000
	s_addc_u32 s5, s19, 0
	s_and_b32 s5, s5, 0xffff
	s_mov_b32 m0, s81
	ds_read_b128 v[164:167], v182 offset:32768
	ds_read_b128 v[168:171], v182 offset:33792
	ds_read_b128 v[172:175], v182 offset:34816
	ds_read_b128 v[186:189], v182 offset:35840
	ds_read_b128 v[190:193], v182 offset:36864
	ds_read_b128 v[194:197], v182 offset:37888
	ds_read_b128 v[198:201], v182 offset:38912
	ds_read_b128 v[202:205], v182 offset:39936
	buffer_load_dwordx4 v176, s[4:7], 0 offen lds
	s_mov_b32 m0, s82
	s_nop 0
	buffer_load_dwordx4 v178, s[4:7], 0 offen lds
	s_waitcnt vmcnt(8)
	s_waitcnt lgkmcnt(0)
	s_barrier
	s_setprio 1
	v_mfma_f32_16x16x32_bf16 v[132:135], v[104:107], v[164:167], v[132:135]
	v_mfma_f32_16x16x32_bf16 v[128:131], v[136:139], v[164:167], v[128:131]
	v_mfma_f32_16x16x32_bf16 v[124:127], v[104:107], v[172:175], v[124:127]
	v_mfma_f32_16x16x32_bf16 v[120:123], v[136:139], v[172:175], v[120:123]
	v_mfma_f32_16x16x32_bf16 v[116:119], v[104:107], v[190:193], v[116:119]
	v_mfma_f32_16x16x32_bf16 v[112:115], v[136:139], v[190:193], v[112:115]
	v_mfma_f32_16x16x32_bf16 v[100:103], v[104:107], v[198:201], v[100:103]
	v_mfma_f32_16x16x32_bf16 v[96:99], v[136:139], v[198:201], v[96:99]
	v_mfma_f32_16x16x32_bf16 v[132:135], v[108:111], v[168:171], v[132:135]
	v_mfma_f32_16x16x32_bf16 v[128:131], v[140:143], v[168:171], v[128:131]
	v_mfma_f32_16x16x32_bf16 v[124:127], v[108:111], v[186:189], v[124:127]
	v_mfma_f32_16x16x32_bf16 v[120:123], v[140:143], v[186:189], v[120:123]
	v_mfma_f32_16x16x32_bf16 v[116:119], v[108:111], v[194:197], v[116:119]
	v_mfma_f32_16x16x32_bf16 v[112:115], v[140:143], v[194:197], v[112:115]
	v_mfma_f32_16x16x32_bf16 v[100:103], v[108:111], v[202:205], v[100:103]
	v_mfma_f32_16x16x32_bf16 v[96:99], v[140:143], v[202:205], v[96:99]
	v_mfma_f32_16x16x32_bf16 v[60:63], v[148:151], v[164:167], v[60:63]
	v_mfma_f32_16x16x32_bf16 v[56:59], v[156:159], v[164:167], v[56:59]
	v_mfma_f32_16x16x32_bf16 v[52:55], v[148:151], v[172:175], v[52:55]
	v_mfma_f32_16x16x32_bf16 v[48:51], v[156:159], v[172:175], v[48:51]
	v_mfma_f32_16x16x32_bf16 v[44:47], v[148:151], v[190:193], v[44:47]
	v_mfma_f32_16x16x32_bf16 v[40:43], v[156:159], v[190:193], v[40:43]
	v_mfma_f32_16x16x32_bf16 v[36:39], v[148:151], v[198:201], v[36:39]
	v_mfma_f32_16x16x32_bf16 v[32:35], v[156:159], v[198:201], v[32:35]
	v_mfma_f32_16x16x32_bf16 v[60:63], v[152:155], v[168:171], v[60:63]
	v_mfma_f32_16x16x32_bf16 v[56:59], v[160:163], v[168:171], v[56:59]
	v_mfma_f32_16x16x32_bf16 v[52:55], v[152:155], v[186:189], v[52:55]
	v_mfma_f32_16x16x32_bf16 v[48:51], v[160:163], v[186:189], v[48:51]
	v_mfma_f32_16x16x32_bf16 v[44:47], v[152:155], v[194:197], v[44:47]
	v_mfma_f32_16x16x32_bf16 v[40:43], v[160:163], v[194:197], v[40:43]
	v_mfma_f32_16x16x32_bf16 v[36:39], v[152:155], v[202:205], v[36:39]
	v_mfma_f32_16x16x32_bf16 v[32:35], v[160:163], v[202:205], v[32:35]
	s_setprio 0
	s_barrier
	s_add_u32 s4, s36, 0x8000
	s_addc_u32 s5, s18, 0
	s_mov_b32 m0, s86
	s_and_b32 s5, s5, 0xffff
	ds_read_b128 v[164:167], v182 offset:49152
	ds_read_b128 v[168:171], v182 offset:50176
	ds_read_b128 v[172:175], v182 offset:51200
	ds_read_b128 v[186:189], v182 offset:52224
	ds_read_b128 v[190:193], v182 offset:53248
	ds_read_b128 v[194:197], v182 offset:54272
	ds_read_b128 v[198:201], v182 offset:55296
	ds_read_b128 v[202:205], v182 offset:56320
	buffer_load_dwordx4 v177, s[4:7], 0 offen lds
	s_mov_b32 m0, s87
	s_mov_b32 s19, s7
	buffer_load_dwordx4 v179, s[4:7], 0 offen lds
	s_add_u32 s4, s36, 0xc000
	s_addc_u32 s5, s18, 0
	s_and_b32 s5, s5, 0xffff
	s_mov_b32 m0, s90
	s_and_b32 s17, s17, 0xffff
	buffer_load_dwordx4 v177, s[4:7], 0 offen lds
	s_mov_b32 m0, s91
	s_mov_b32 s18, s6
	buffer_load_dwordx4 v179, s[4:7], 0 offen lds
	s_mov_b32 m0, s88
	s_nop 0
	buffer_load_dwordx4 v176, s[16:19], 0 offen lds
	s_mov_b32 m0, s89
	s_nop 0
	buffer_load_dwordx4 v178, s[16:19], 0 offen lds
	s_waitcnt vmcnt(8)
	s_waitcnt lgkmcnt(0)
	s_barrier
	s_setprio 1
	v_mfma_f32_16x16x32_bf16 v[92:95], v[104:107], v[164:167], v[92:95]
	v_mfma_f32_16x16x32_bf16 v[88:91], v[136:139], v[164:167], v[88:91]
	v_mfma_f32_16x16x32_bf16 v[84:87], v[104:107], v[172:175], v[84:87]
	v_mfma_f32_16x16x32_bf16 v[80:83], v[136:139], v[172:175], v[80:83]
	v_mfma_f32_16x16x32_bf16 v[76:79], v[104:107], v[190:193], v[76:79]
	v_mfma_f32_16x16x32_bf16 v[72:75], v[136:139], v[190:193], v[72:75]
	v_mfma_f32_16x16x32_bf16 v[68:71], v[104:107], v[198:201], v[68:71]
	v_mfma_f32_16x16x32_bf16 v[64:67], v[136:139], v[198:201], v[64:67]
	v_mfma_f32_16x16x32_bf16 v[92:95], v[108:111], v[168:171], v[92:95]
	v_mfma_f32_16x16x32_bf16 v[88:91], v[140:143], v[168:171], v[88:91]
	v_mfma_f32_16x16x32_bf16 v[84:87], v[108:111], v[186:189], v[84:87]
	v_mfma_f32_16x16x32_bf16 v[80:83], v[140:143], v[186:189], v[80:83]
	v_mfma_f32_16x16x32_bf16 v[76:79], v[108:111], v[194:197], v[76:79]
	v_mfma_f32_16x16x32_bf16 v[72:75], v[140:143], v[194:197], v[72:75]
	v_mfma_f32_16x16x32_bf16 v[68:71], v[108:111], v[202:205], v[68:71]
	v_mfma_f32_16x16x32_bf16 v[64:67], v[140:143], v[202:205], v[64:67]
	v_mfma_f32_16x16x32_bf16 v[28:31], v[148:151], v[164:167], v[28:31]
	v_mfma_f32_16x16x32_bf16 v[24:27], v[156:159], v[164:167], v[24:27]
	v_mfma_f32_16x16x32_bf16 v[20:23], v[148:151], v[172:175], v[20:23]
	v_mfma_f32_16x16x32_bf16 v[16:19], v[156:159], v[172:175], v[16:19]
	v_mfma_f32_16x16x32_bf16 v[12:15], v[148:151], v[190:193], v[12:15]
	v_mfma_f32_16x16x32_bf16 v[8:11], v[156:159], v[190:193], v[8:11]
	v_mfma_f32_16x16x32_bf16 v[4:7], v[148:151], v[198:201], v[4:7]
	v_mfma_f32_16x16x32_bf16 v[0:3], v[156:159], v[198:201], v[0:3]
	v_mfma_f32_16x16x32_bf16 v[28:31], v[152:155], v[168:171], v[28:31]
	v_mfma_f32_16x16x32_bf16 v[24:27], v[160:163], v[168:171], v[24:27]
	v_mfma_f32_16x16x32_bf16 v[20:23], v[152:155], v[186:189], v[20:23]
	v_mfma_f32_16x16x32_bf16 v[16:19], v[160:163], v[186:189], v[16:19]
	v_mfma_f32_16x16x32_bf16 v[12:15], v[152:155], v[194:197], v[12:15]
	v_mfma_f32_16x16x32_bf16 v[8:11], v[160:163], v[194:197], v[8:11]
	v_mfma_f32_16x16x32_bf16 v[4:7], v[152:155], v[202:205], v[4:7]
	v_mfma_f32_16x16x32_bf16 v[0:3], v[160:163], v[202:205], v[0:3]
	s_setprio 0
	s_barrier
	s_add_u32 s63, s63, 0x10000
	s_addc_u32 vcc_lo, vcc_lo, 0
	s_add_u32 vcc_hi, vcc_hi, 0x100
	s_addc_u32 s35, s35, 0
	s_cmp_ge_i32 s64, s9
	s_mov_b32 s4, s64
	s_cbranch_scc0 .LBB0_408
	s_and_b64 vcc, exec, s[66:67]
	s_cbranch_vccz .LBB0_411
	s_barrier

; #define PG8_STAGE(bufoff, gbase, voff) do { const __amdgpu_buffer_rsrc_t _rs = __builtin_amdgcn_make_buffer_rsrc((void*)(gbase), 0, 0x7fffffff, 0x00020000); _Pragma("unroll") for (int _i = 0; _i < 2; ++_i) \
;         __builtin_amdgcn_raw_ptr_buffer_load_lds(_rs, (LAS unsigned*)(lds + (bufoff) + ldsw + _i * 8192), 16, (int)(voff)[_i], 0, 0, 0); } while (0)
; #define PG8_WAIT_V(n) asm volatile("s_waitcnt vmcnt(" #n ")" ::: "memory")
; #define PG8_WAIT_L(n) asm volatile("s_waitcnt lgkmcnt(" #n ")" ::: "memory")
; #define PG8_BAR __builtin_amdgcn_s_barrier()
; #define PG8_SCHED __builtin_amdgcn_sched_barrier(0)
; template <class Epi, class Sched, bool F8 = false>
; __device__ __forceinline__ void gemm_phase(LAS unsigned char* lds, const int lda, const int ldb, const Sched& S, const Epi& E) {
;     ...
;             PG8_LDB(B0, 0, 0); PG8_LDB(B1, 0, 1); PG8_SCHED; PG8_LDA(At, 0, 0); PG8_STAGE(PG8_SA(1, 1), a1 + hstepA, voffA);
;             PG8_WAIT_V(8); PG8_WAIT_L(0); PG8_BAR; PG8_MMA(0, 0, At, B0); PG8_MMA(0, 1, At, B1); PG8_BAR; PG8_SCHED;
;             PG8_LDA(At, 0, 1); PG8_STAGE(PG8_SB(0, 0), b2, voffB); PG8_STAGE(PG8_SB(0, 1), b2 + hstepB, voffB); PG8_STAGE(PG8_SA(0, 0), a2, voffA);
;             PG8_WAIT_V(8); PG8_WAIT_L(0); PG8_BAR; PG8_MMA(1, 0, At, B0); PG8_MMA(1, 1, At, B1); PG8_BAR; PG8_SCHED;
.LBB0_485:
	v_add_u32_e32 v144, 0x10000, v152
	v_add_u32_e32 v166, 0x14000, v152
	ds_read_b128 v[132:135], v144
	ds_read_b128 v[136:139], v144 offset:1024
	ds_read_b128 v[140:143], v144 offset:2048
	ds_read_b128 v[144:147], v144 offset:3072
	ds_read_b128 v[154:157], v166
	ds_read_b128 v[158:161], v166 offset:1024
	ds_read_b128 v[162:165], v166 offset:2048
	ds_read_b128 v[166:169], v166 offset:3072
	s_add_u32 s4, s47, 0xfff80080
	s_addc_u32 s5, s62, -1
	s_cmp_eq_u32 s63, 28
	s_cselect_b32 s40, s48, s4
	s_cselect_b32 s19, s49, s5
	s_cselect_b32 s18, s51, s33
	s_cselect_b32 s36, s50, s9
	s_add_u32 s16, s40, 0x80
	s_addc_u32 s17, s19, 0
	s_and_b32 s5, s62, 0xffff
	s_mov_b32 s4, s47
	s_mov_b32 m0, s91
	ds_read_b128 v[170:173], v153
	ds_read_b128 v[174:177], v153 offset:1024
	ds_read_b128 v[178:181], v153 offset:2048
	ds_read_b128 v[182:185], v153 offset:3072
	ds_read_b128 v[186:189], v153 offset:4096
	ds_read_b128 v[190:193], v153 offset:5120
	ds_read_b128 v[194:197], v153 offset:6144
	ds_read_b128 v[198:201], v153 offset:7168
	buffer_load_dwordx4 v148, s[4:7], 0 offen lds
	s_mov_b32 m0, s92
	s_nop 0
	buffer_load_dwordx4 v150, s[4:7], 0 offen lds
	s_waitcnt vmcnt(8)
	s_waitcnt lgkmcnt(0)
	s_barrier
	s_setprio 1
	v_mfma_f32_16x16x32_bf16 v[124:127], v[132:135], v[170:173], v[124:127]
	v_mfma_f32_16x16x32_bf16 v[120:123], v[140:143], v[170:173], v[120:123]
	v_mfma_f32_16x16x32_bf16 v[116:119], v[132:135], v[178:181], v[116:119]
	v_mfma_f32_16x16x32_bf16 v[112:115], v[140:143], v[178:181], v[112:115]
	v_mfma_f32_16x16x32_bf16 v[108:111], v[132:135], v[186:189], v[108:111]
	v_mfma_f32_16x16x32_bf16 v[104:107], v[140:143], v[186:189], v[104:107]
	v_mfma_f32_16x16x32_bf16 v[100:103], v[132:135], v[194:197], v[100:103]
	v_mfma_f32_16x16x32_bf16 v[96:99], v[140:143], v[194:197], v[96:99]
	v_mfma_f32_16x16x32_bf16 v[124:127], v[136:139], v[174:177], v[124:127]
	v_mfma_f32_16x16x32_bf16 v[120:123], v[144:147], v[174:177], v[120:123]
	v_mfma_f32_16x16x32_bf16 v[116:119], v[136:139], v[182:185], v[116:119]
	v_mfma_f32_16x16x32_bf16 v[112:115], v[144:147], v[182:185], v[112:115]
	v_mfma_f32_16x16x32_bf16 v[108:111], v[136:139], v[190:193], v[108:111]
	v_mfma_f32_16x16x32_bf16 v[104:107], v[144:147], v[190:193], v[104:107]
	v_mfma_f32_16x16x32_bf16 v[100:103], v[136:139], v[198:201], v[100:103]
	v_mfma_f32_16x16x32_bf16 v[96:99], v[144:147], v[198:201], v[96:99]
	v_mfma_f32_16x16x32_bf16 v[92:95], v[154:157], v[170:173], v[92:95]
	v_mfma_f32_16x16x32_bf16 v[88:91], v[162:165], v[170:173], v[88:91]
	v_mfma_f32_16x16x32_bf16 v[84:87], v[154:157], v[178:181], v[84:87]
	v_mfma_f32_16x16x32_bf16 v[80:83], v[162:165], v[178:181], v[80:83]
	v_mfma_f32_16x16x32_bf16 v[76:79], v[154:157], v[186:189], v[76:79]
	v_mfma_f32_16x16x32_bf16 v[72:75], v[162:165], v[186:189], v[72:75]
	v_mfma_f32_16x16x32_bf16 v[68:71], v[154:157], v[194:197], v[68:71]
	v_mfma_f32_16x16x32_bf16 v[64:67], v[162:165], v[194:197], v[64:67]
	v_mfma_f32_16x16x32_bf16 v[92:95], v[158:161], v[174:177], v[92:95]
	v_mfma_f32_16x16x32_bf16 v[88:91], v[166:169], v[174:177], v[88:91]
	v_mfma_f32_16x16x32_bf16 v[84:87], v[158:161], v[182:185], v[84:87]
	v_mfma_f32_16x16x32_bf16 v[80:83], v[166:169], v[182:185], v[80:83]
	v_mfma_f32_16x16x32_bf16 v[76:79], v[158:161], v[190:193], v[76:79]
	v_mfma_f32_16x16x32_bf16 v[72:75], v[166:169], v[190:193], v[72:75]
	v_mfma_f32_16x16x32_bf16 v[68:71], v[158:161], v[198:201], v[68:71]
	v_mfma_f32_16x16x32_bf16 v[64:67], v[166:169], v[198:201], v[64:67]
	s_setprio 0
	s_barrier
	s_and_b32 s37, s18, 0xffff
	s_mov_b32 m0, s70
	s_mov_b32 s38, s6
	s_mov_b32 s39, s7
	s_add_u32 s4, s36, 0x4000
	ds_read_b128 v[170:173], v153 offset:16384
	ds_read_b128 v[174:177], v153 offset:17408
	ds_read_b128 v[178:181], v153 offset:18432
	ds_read_b128 v[182:185], v153 offset:19456
	ds_read_b128 v[186:189], v153 offset:20480
	ds_read_b128 v[190:193], v153 offset:21504
	ds_read_b128 v[194:197], v153 offset:22528
	ds_read_b128 v[198:201], v153 offset:23552
	buffer_load_dwordx4 v149, s[36:39], 0 offen lds
	s_mov_b32 m0, s71
	s_addc_u32 s5, s18, 0
	buffer_load_dwordx4 v151, s[36:39], 0 offen lds
	s_and_b32 s5, s5, 0xffff
	s_mov_b32 m0, s72
	s_and_b32 s41, s19, 0xffff
	buffer_load_dwordx4 v149, s[4:7], 0 offen lds
	s_mov_b32 m0, s73
	s_mov_b32 s42, s6
	buffer_load_dwordx4 v151, s[4:7], 0 offen lds
	s_mov_b32 s43, s7
	s_mov_b32 m0, s67
	s_nop 0
	buffer_load_dwordx4 v148, s[40:43], 0 offen lds
	s_mov_b32 m0, s74
	s_nop 0
	buffer_load_dwordx4 v150, s[40:43], 0 offen lds
	s_waitcnt vmcnt(8)
	s_waitcnt lgkmcnt(0)
	s_barrier
; #define PG8_STAGE(bufoff, gbase, voff) do { const __amdgpu_buffer_rsrc_t _rs = __builtin_amdgcn_make_buffer_rsrc((void*)(gbase), 0, 0x7fffffff, 0x00020000); _Pragma("unroll") for (int _i = 0; _i < 2; ++_i) \
;         __builtin_amdgcn_raw_ptr_buffer_load_lds(_rs, (LAS unsigned*)(lds + (bufoff) + ldsw + _i * 8192), 16, (int)(voff)[_i], 0, 0, 0); } while (0)
; #define PG8_WAIT_V(n) asm volatile("s_waitcnt vmcnt(" #n ")" ::: "memory")
; #define PG8_WAIT_L(n) asm volatile("s_waitcnt lgkmcnt(" #n ")" ::: "memory")
; #define PG8_BAR __builtin_amdgcn_s_barrier()
; #define PG8_SCHED __builtin_amdgcn_sched_barrier(0)
; template <class Epi, class Sched, bool F8 = false>
; __device__ __forceinline__ void gemm_phase(LAS unsigned char* lds, const int lda, const int ldb, const Sched& S, const Epi& E) {
;     ...
;             PG8_LDA(At, 0, 1); PG8_STAGE(PG8_SB(0, 0), b2, voffB); PG8_STAGE(PG8_SB(0, 1), b2 + hstepB, voffB); PG8_STAGE(PG8_SA(0, 0), a2, voffA);
;             PG8_WAIT_V(8); PG8_WAIT_L(0); PG8_BAR; PG8_MMA(1, 0, At, B0); PG8_MMA(1, 1, At, B1); PG8_BAR; PG8_SCHED;
;             PG8_LDB(B0, 1, 0); PG8_LDB(B1, 1, 1); PG8_SCHED; PG8_LDA(At, 1, 0); PG8_STAGE(PG8_SA(0, 1), a2 + hstepA, voffA);
;             PG8_WAIT_V(8); PG8_WAIT_L(0); PG8_BAR; PG8_MMA(0, 0, At, B0); PG8_MMA(0, 1, At, B1); PG8_BAR; PG8_SCHED;
	s_setprio 1
	v_mfma_f32_16x16x32_bf16 v[60:63], v[132:135], v[170:173], v[60:63]
	v_mfma_f32_16x16x32_bf16 v[56:59], v[140:143], v[170:173], v[56:59]
	v_mfma_f32_16x16x32_bf16 v[52:55], v[132:135], v[178:181], v[52:55]
	v_mfma_f32_16x16x32_bf16 v[48:51], v[140:143], v[178:181], v[48:51]
	v_mfma_f32_16x16x32_bf16 v[44:47], v[132:135], v[186:189], v[44:47]
	v_mfma_f32_16x16x32_bf16 v[40:43], v[140:143], v[186:189], v[40:43]
	v_mfma_f32_16x16x32_bf16 v[36:39], v[132:135], v[194:197], v[36:39]
	v_mfma_f32_16x16x32_bf16 v[32:35], v[140:143], v[194:197], v[32:35]
	v_mfma_f32_16x16x32_bf16 v[60:63], v[136:139], v[174:177], v[60:63]
	v_mfma_f32_16x16x32_bf16 v[56:59], v[144:147], v[174:177], v[56:59]
	v_mfma_f32_16x16x32_bf16 v[52:55], v[136:139], v[182:185], v[52:55]
	v_mfma_f32_16x16x32_bf16 v[48:51], v[144:147], v[182:185], v[48:51]
	v_mfma_f32_16x16x32_bf16 v[44:47], v[136:139], v[190:193], v[44:47]
	v_mfma_f32_16x16x32_bf16 v[40:43], v[144:147], v[190:193], v[40:43]
	v_mfma_f32_16x16x32_bf16 v[36:39], v[136:139], v[198:201], v[36:39]
	v_mfma_f32_16x16x32_bf16 v[32:35], v[144:147], v[198:201], v[32:35]
	v_mfma_f32_16x16x32_bf16 v[28:31], v[154:157], v[170:173], v[28:31]
	v_mfma_f32_16x16x32_bf16 v[24:27], v[162:165], v[170:173], v[24:27]
	v_mfma_f32_16x16x32_bf16 v[20:23], v[154:157], v[178:181], v[20:23]
	v_mfma_f32_16x16x32_bf16 v[16:19], v[162:165], v[178:181], v[16:19]
	v_mfma_f32_16x16x32_bf16 v[12:15], v[154:157], v[186:189], v[12:15]
	v_mfma_f32_16x16x32_bf16 v[8:11], v[162:165], v[186:189], v[8:11]
	v_mfma_f32_16x16x32_bf16 v[4:7], v[154:157], v[194:197], v[4:7]
	v_mfma_f32_16x16x32_bf16 v[0:3], v[162:165], v[194:197], v[0:3]
	v_mfma_f32_16x16x32_bf16 v[28:31], v[158:161], v[174:177], v[28:31]
	v_mfma_f32_16x16x32_bf16 v[24:27], v[166:169], v[174:177], v[24:27]
	v_mfma_f32_16x16x32_bf16 v[20:23], v[158:161], v[182:185], v[20:23]
	v_mfma_f32_16x16x32_bf16 v[16:19], v[166:169], v[182:185], v[16:19]
	v_mfma_f32_16x16x32_bf16 v[12:15], v[158:161], v[190:193], v[12:15]
	v_mfma_f32_16x16x32_bf16 v[8:11], v[166:169], v[190:193], v[8:11]
	v_mfma_f32_16x16x32_bf16 v[4:7], v[158:161], v[198:201], v[4:7]
	v_mfma_f32_16x16x32_bf16 v[0:3], v[166:169], v[198:201], v[0:3]
	s_setprio 0
	s_barrier
	v_add_u32_e32 v144, 0x18000, v152
	v_add_u32_e32 v166, 0x1c000, v152
	ds_read_b128 v[132:135], v144
	ds_read_b128 v[136:139], v144 offset:1024
	ds_read_b128 v[140:143], v144 offset:2048
	ds_read_b128 v[144:147], v144 offset:3072
	ds_read_b128 v[154:157], v166
	ds_read_b128 v[158:161], v166 offset:1024
	ds_read_b128 v[162:165], v166 offset:2048
	ds_read_b128 v[166:169], v166 offset:3072
	s_add_u32 s4, s40, 0x80000
	s_addc_u32 s5, s19, 0
	s_and_b32 s5, s5, 0xffff
	s_mov_b32 m0, s75
	ds_read_b128 v[170:173], v153 offset:32768
	ds_read_b128 v[174:177], v153 offset:33792
	ds_read_b128 v[178:181], v153 offset:34816
	ds_read_b128 v[182:185], v153 offset:35840
	ds_read_b128 v[186:189], v153 offset:36864
	ds_read_b128 v[190:193], v153 offset:37888
	ds_read_b128 v[194:197], v153 offset:38912
	ds_read_b128 v[198:201], v153 offset:39936
	buffer_load_dwordx4 v148, s[4:7], 0 offen lds
	s_mov_b32 m0, s76
	s_nop 0
	buffer_load_dwordx4 v150, s[4:7], 0 offen lds
	s_waitcnt vmcnt(8)
	s_waitcnt lgkmcnt(0)
	s_barrier
	s_setprio 1
	v_mfma_f32_16x16x32_bf16 v[124:127], v[132:135], v[170:173], v[124:127]
	v_mfma_f32_16x16x32_bf16 v[120:123], v[140:143], v[170:173], v[120:123]
	v_mfma_f32_16x16x32_bf16 v[116:119], v[132:135], v[178:181], v[116:119]
	v_mfma_f32_16x16x32_bf16 v[112:115], v[140:143], v[178:181], v[112:115]
	v_mfma_f32_16x16x32_bf16 v[108:111], v[132:135], v[186:189], v[108:111]
	v_mfma_f32_16x16x32_bf16 v[104:107], v[140:143], v[186:189], v[104:107]
	v_mfma_f32_16x16x32_bf16 v[100:103], v[132:135], v[194:197], v[100:103]
	v_mfma_f32_16x16x32_bf16 v[96:99], v[140:143], v[194:197], v[96:99]
	v_mfma_f32_16x16x32_bf16 v[124:127], v[136:139], v[174:177], v[124:127]
	v_mfma_f32_16x16x32_bf16 v[120:123], v[144:147], v[174:177], v[120:123]
	v_mfma_f32_16x16x32_bf16 v[116:119], v[136:139], v[182:185], v[116:119]
	v_mfma_f32_16x16x32_bf16 v[112:115], v[144:147], v[182:185], v[112:115]
	v_mfma_f32_16x16x32_bf16 v[108:111], v[136:139], v[190:193], v[108:111]
	v_mfma_f32_16x16x32_bf16 v[104:107], v[144:147], v[190:193], v[104:107]
	v_mfma_f32_16x16x32_bf16 v[100:103], v[136:139], v[198:201], v[100:103]
	v_mfma_f32_16x16x32_bf16 v[96:99], v[144:147], v[198:201], v[96:99]
	v_mfma_f32_16x16x32_bf16 v[92:95], v[154:157], v[170:173], v[92:95]
	v_mfma_f32_16x16x32_bf16 v[88:91], v[162:165], v[170:173], v[88:91]
	v_mfma_f32_16x16x32_bf16 v[84:87], v[154:157], v[178:181], v[84:87]
	v_mfma_f32_16x16x32_bf16 v[80:83], v[162:165], v[178:181], v[80:83]
	v_mfma_f32_16x16x32_bf16 v[76:79], v[154:157], v[186:189], v[76:79]
	v_mfma_f32_16x16x32_bf16 v[72:75], v[162:165], v[186:189], v[72:75]
	v_mfma_f32_16x16x32_bf16 v[68:71], v[154:157], v[194:197], v[68:71]
	v_mfma_f32_16x16x32_bf16 v[64:67], v[162:165], v[194:197], v[64:67]
	v_mfma_f32_16x16x32_bf16 v[92:95], v[158:161], v[174:177], v[92:95]
	v_mfma_f32_16x16x32_bf16 v[88:91], v[166:169], v[174:177], v[88:91]
	v_mfma_f32_16x16x32_bf16 v[84:87], v[158:161], v[182:185], v[84:87]
	v_mfma_f32_16x16x32_bf16 v[80:83], v[166:169], v[182:185], v[80:83]
	v_mfma_f32_16x16x32_bf16 v[76:79], v[158:161], v[190:193], v[76:79]
	v_mfma_f32_16x16x32_bf16 v[72:75], v[166:169], v[190:193], v[72:75]
	v_mfma_f32_16x16x32_bf16 v[68:71], v[158:161], v[198:201], v[68:71]
	v_mfma_f32_16x16x32_bf16 v[64:67], v[166:169], v[198:201], v[64:67]
	s_setprio 0
	s_barrier
; #define PG8_STAGE(bufoff, gbase, voff) do { const __amdgpu_buffer_rsrc_t _rs = __builtin_amdgcn_make_buffer_rsrc((void*)(gbase), 0, 0x7fffffff, 0x00020000); _Pragma("unroll") for (int _i = 0; _i < 2; ++_i) \
;         __builtin_amdgcn_raw_ptr_buffer_load_lds(_rs, (LAS unsigned*)(lds + (bufoff) + ldsw + _i * 8192), 16, (int)(voff)[_i], 0, 0, 0); } while (0)
; #define PG8_WAIT_V(n) asm volatile("s_waitcnt vmcnt(" #n ")" ::: "memory")
; #define PG8_WAIT_L(n) asm volatile("s_waitcnt lgkmcnt(" #n ")" ::: "memory")
; #define PG8_BAR __builtin_amdgcn_s_barrier()
; #define PG8_SCHED __builtin_amdgcn_sched_barrier(0)
; template <class Epi, class Sched, bool F8 = false>
; __device__ __forceinline__ void gemm_phase(LAS unsigned char* lds, const int lda, const int ldb, const Sched& S, const Epi& E) {
;     ...
;             PG8_LDA(At, 1, 1); PG8_STAGE(PG8_SB(1, 0), b3, voffB); PG8_STAGE(PG8_SB(1, 1), b3 + hstepB, voffB); PG8_STAGE(PG8_SA(1, 0), a3, voffA);
;             PG8_WAIT_V(8); PG8_WAIT_L(0); PG8_BAR; PG8_MMA(1, 0, At, B0); PG8_MMA(1, 1, At, B1); PG8_BAR; PG8_SCHED;
	s_add_u32 s4, s36, 0x8000
	s_addc_u32 s5, s18, 0
	s_mov_b32 m0, s85
	s_and_b32 s5, s5, 0xffff
	ds_read_b128 v[170:173], v153 offset:49152
	ds_read_b128 v[174:177], v153 offset:50176
	ds_read_b128 v[178:181], v153 offset:51200
	ds_read_b128 v[182:185], v153 offset:52224
	ds_read_b128 v[186:189], v153 offset:53248
	ds_read_b128 v[190:193], v153 offset:54272
	ds_read_b128 v[194:197], v153 offset:55296
	ds_read_b128 v[198:201], v153 offset:56320
	buffer_load_dwordx4 v149, s[4:7], 0 offen lds
	s_mov_b32 m0, s86
	s_mov_b32 s19, s7
	buffer_load_dwordx4 v151, s[4:7], 0 offen lds
	s_add_u32 s4, s36, 0xc000
	s_addc_u32 s5, s18, 0
	s_and_b32 s5, s5, 0xffff
	s_mov_b32 m0, s89
	s_and_b32 s17, s17, 0xffff
	buffer_load_dwordx4 v149, s[4:7], 0 offen lds
	s_mov_b32 m0, s90
	s_mov_b32 s18, s6
	buffer_load_dwordx4 v151, s[4:7], 0 offen lds
	s_mov_b32 m0, s87
	s_nop 0
	buffer_load_dwordx4 v148, s[16:19], 0 offen lds
	s_mov_b32 m0, s88
	s_nop 0
	buffer_load_dwordx4 v150, s[16:19], 0 offen lds
	s_waitcnt vmcnt(8)
	s_waitcnt lgkmcnt(0)
	s_barrier
	s_setprio 1
	v_mfma_f32_16x16x32_bf16 v[60:63], v[132:135], v[170:173], v[60:63]
	v_mfma_f32_16x16x32_bf16 v[56:59], v[140:143], v[170:173], v[56:59]
	v_mfma_f32_16x16x32_bf16 v[52:55], v[132:135], v[178:181], v[52:55]
	v_mfma_f32_16x16x32_bf16 v[48:51], v[140:143], v[178:181], v[48:51]
	v_mfma_f32_16x16x32_bf16 v[44:47], v[132:135], v[186:189], v[44:47]
	v_mfma_f32_16x16x32_bf16 v[40:43], v[140:143], v[186:189], v[40:43]
	v_mfma_f32_16x16x32_bf16 v[36:39], v[132:135], v[194:197], v[36:39]
	v_mfma_f32_16x16x32_bf16 v[32:35], v[140:143], v[194:197], v[32:35]
	v_mfma_f32_16x16x32_bf16 v[60:63], v[136:139], v[174:177], v[60:63]
	v_mfma_f32_16x16x32_bf16 v[56:59], v[144:147], v[174:177], v[56:59]
	v_mfma_f32_16x16x32_bf16 v[52:55], v[136:139], v[182:185], v[52:55]
	v_mfma_f32_16x16x32_bf16 v[48:51], v[144:147], v[182:185], v[48:51]
	v_mfma_f32_16x16x32_bf16 v[44:47], v[136:139], v[190:193], v[44:47]
	v_mfma_f32_16x16x32_bf16 v[40:43], v[144:147], v[190:193], v[40:43]
	v_mfma_f32_16x16x32_bf16 v[36:39], v[136:139], v[198:201], v[36:39]
	v_mfma_f32_16x16x32_bf16 v[32:35], v[144:147], v[198:201], v[32:35]
	v_mfma_f32_16x16x32_bf16 v[28:31], v[154:157], v[170:173], v[28:31]
	v_mfma_f32_16x16x32_bf16 v[24:27], v[162:165], v[170:173], v[24:27]
	v_mfma_f32_16x16x32_bf16 v[20:23], v[154:157], v[178:181], v[20:23]
	v_mfma_f32_16x16x32_bf16 v[16:19], v[162:165], v[178:181], v[16:19]
	v_mfma_f32_16x16x32_bf16 v[12:15], v[154:157], v[186:189], v[12:15]
	v_mfma_f32_16x16x32_bf16 v[8:11], v[162:165], v[186:189], v[8:11]
	v_mfma_f32_16x16x32_bf16 v[4:7], v[154:157], v[194:197], v[4:7]
	v_mfma_f32_16x16x32_bf16 v[0:3], v[162:165], v[194:197], v[0:3]
	v_mfma_f32_16x16x32_bf16 v[28:31], v[158:161], v[174:177], v[28:31]
	v_mfma_f32_16x16x32_bf16 v[24:27], v[166:169], v[174:177], v[24:27]
	v_mfma_f32_16x16x32_bf16 v[20:23], v[158:161], v[182:185], v[20:23]
	v_mfma_f32_16x16x32_bf16 v[16:19], v[166:169], v[182:185], v[16:19]
	v_mfma_f32_16x16x32_bf16 v[12:15], v[158:161], v[190:193], v[12:15]
	v_mfma_f32_16x16x32_bf16 v[8:11], v[166:169], v[190:193], v[8:11]
	v_mfma_f32_16x16x32_bf16 v[4:7], v[158:161], v[198:201], v[4:7]
	v_mfma_f32_16x16x32_bf16 v[0:3], v[166:169], v[198:201], v[0:3]
	s_setprio 0
	s_barrier
	s_add_i32 s63, s63, 2
	s_add_u32 s9, s9, 0x10000
	s_addc_u32 s33, s33, 0
	s_add_u32 s47, s47, 0x100
	s_addc_u32 s62, s62, 0
	s_cmp_gt_u32 s63, 29
	s_cbranch_scc0 .LBB0_485
	s_and_b64 vcc, exec, s[44:45]
	s_cbranch_vccz .LBB0_488
	s_barrier

; #define PG8_STAGE(bufoff, gbase, voff) do { const __amdgpu_buffer_rsrc_t _rs = __builtin_amdgcn_make_buffer_rsrc((void*)(gbase), 0, 0x7fffffff, 0x00020000); _Pragma("unroll") for (int _i = 0; _i < 2; ++_i) \
;         __builtin_amdgcn_raw_ptr_buffer_load_lds(_rs, (LAS unsigned*)(lds + (bufoff) + ldsw + _i * 8192), 16, (int)(voff)[_i], 0, 0, 0); } while (0)
; #define PG8_WAIT_V(n) asm volatile("s_waitcnt vmcnt(" #n ")" ::: "memory")
; #define PG8_WAIT_L(n) asm volatile("s_waitcnt lgkmcnt(" #n ")" ::: "memory")
; #define PG8_BAR __builtin_amdgcn_s_barrier()
; #define PG8_SCHED __builtin_amdgcn_sched_barrier(0)
; template <class Epi, class Sched, bool F8 = false>
; __device__ __forceinline__ void gemm_phase(LAS unsigned char* lds, const int lda, const int ldb, const Sched& S, const Epi& E) {
;     ...
;             PG8_LDB(B0, 0, 0); PG8_LDB(B1, 0, 1); PG8_SCHED; PG8_LDA(At, 0, 0); PG8_STAGE(PG8_SA(1, 1), a1 + hstepA, voffA);
;             PG8_WAIT_V(8); PG8_WAIT_L(0); PG8_BAR; PG8_MMA(0, 0, At, B0); PG8_MMA(0, 1, At, B1); PG8_BAR; PG8_SCHED;
;             PG8_LDA(At, 0, 1); PG8_STAGE(PG8_SB(0, 0), b2, voffB); PG8_STAGE(PG8_SB(0, 1), b2 + hstepB, voffB); PG8_STAGE(PG8_SA(0, 0), a2, voffA);
;             PG8_WAIT_V(8); PG8_WAIT_L(0); PG8_BAR; PG8_MMA(1, 0, At, B0); PG8_MMA(1, 1, At, B1); PG8_BAR; PG8_SCHED;
.LBB0_632:
	ds_read_b128 v[132:135], v142
	ds_read_b128 v[148:151], v142 offset:1024
	ds_read_b128 v[152:155], v142 offset:2048
	ds_read_b128 v[156:159], v142 offset:3072
	ds_read_b128 v[160:163], v143
	ds_read_b128 v[164:167], v143 offset:1024
	ds_read_b128 v[168:171], v143 offset:2048
	ds_read_b128 v[172:175], v143 offset:3072
	s_add_u32 s4, vcc_lo, 0xfff00080
	s_addc_u32 s5, vcc_hi, -1
	s_cmp_eq_u32 s64, 60
	s_cselect_b32 s40, s68, s4
	s_cselect_b32 s19, s69, s5
	s_cselect_b32 s18, s71, s67
	s_cselect_b32 s36, s70, s51
	s_add_u32 s16, s40, 0x80
	s_addc_u32 s17, s19, 0
	s_and_b32 s5, vcc_hi, 0xffff
	s_mov_b32 s4, vcc_lo
	s_mov_b32 m0, s92
	ds_read_b128 v[176:179], v144
	ds_read_b128 v[180:183], v144 offset:1024
	ds_read_b128 v[184:187], v144 offset:2048
	ds_read_b128 v[188:191], v144 offset:3072
	ds_read_b128 v[192:195], v144 offset:4096
	ds_read_b128 v[196:199], v144 offset:5120
	ds_read_b128 v[200:203], v144 offset:6144
	ds_read_b128 v[204:207], v144 offset:7168
	buffer_load_dwordx4 v138, s[4:7], 0 offen lds
	s_mov_b32 m0, s93
	s_nop 0
	buffer_load_dwordx4 v140, s[4:7], 0 offen lds
	s_waitcnt vmcnt(8)
	s_waitcnt lgkmcnt(0)
	s_barrier
	s_setprio 1
	v_mfma_f32_16x16x32_bf16 v[124:127], v[132:135], v[176:179], v[124:127]
	v_mfma_f32_16x16x32_bf16 v[120:123], v[152:155], v[176:179], v[120:123]
	v_mfma_f32_16x16x32_bf16 v[108:111], v[132:135], v[184:187], v[108:111]
	v_mfma_f32_16x16x32_bf16 v[104:107], v[152:155], v[184:187], v[104:107]
	v_mfma_f32_16x16x32_bf16 v[92:95], v[132:135], v[192:195], v[92:95]
	v_mfma_f32_16x16x32_bf16 v[88:91], v[152:155], v[192:195], v[88:91]
	v_mfma_f32_16x16x32_bf16 v[76:79], v[132:135], v[200:203], v[76:79]
	v_mfma_f32_16x16x32_bf16 v[72:75], v[152:155], v[200:203], v[72:75]
	v_mfma_f32_16x16x32_bf16 v[124:127], v[148:151], v[180:183], v[124:127]
	v_mfma_f32_16x16x32_bf16 v[120:123], v[156:159], v[180:183], v[120:123]
	v_mfma_f32_16x16x32_bf16 v[108:111], v[148:151], v[188:191], v[108:111]
	v_mfma_f32_16x16x32_bf16 v[104:107], v[156:159], v[188:191], v[104:107]
	v_mfma_f32_16x16x32_bf16 v[92:95], v[148:151], v[196:199], v[92:95]
	v_mfma_f32_16x16x32_bf16 v[88:91], v[156:159], v[196:199], v[88:91]
	v_mfma_f32_16x16x32_bf16 v[76:79], v[148:151], v[204:207], v[76:79]
	v_mfma_f32_16x16x32_bf16 v[72:75], v[156:159], v[204:207], v[72:75]
	v_mfma_f32_16x16x32_bf16 v[116:119], v[160:163], v[176:179], v[116:119]
	v_mfma_f32_16x16x32_bf16 v[112:115], v[168:171], v[176:179], v[112:115]
	v_mfma_f32_16x16x32_bf16 v[100:103], v[160:163], v[184:187], v[100:103]
	v_mfma_f32_16x16x32_bf16 v[96:99], v[168:171], v[184:187], v[96:99]
	v_mfma_f32_16x16x32_bf16 v[84:87], v[160:163], v[192:195], v[84:87]
	v_mfma_f32_16x16x32_bf16 v[80:83], v[168:171], v[192:195], v[80:83]
	v_mfma_f32_16x16x32_bf16 v[68:71], v[160:163], v[200:203], v[68:71]
	v_mfma_f32_16x16x32_bf16 v[64:67], v[168:171], v[200:203], v[64:67]
	v_mfma_f32_16x16x32_bf16 v[116:119], v[164:167], v[180:183], v[116:119]
	v_mfma_f32_16x16x32_bf16 v[112:115], v[172:175], v[180:183], v[112:115]
	v_mfma_f32_16x16x32_bf16 v[100:103], v[164:167], v[188:191], v[100:103]
	v_mfma_f32_16x16x32_bf16 v[96:99], v[172:175], v[188:191], v[96:99]
	v_mfma_f32_16x16x32_bf16 v[84:87], v[164:167], v[196:199], v[84:87]
	v_mfma_f32_16x16x32_bf16 v[80:83], v[172:175], v[196:199], v[80:83]
	v_mfma_f32_16x16x32_bf16 v[68:71], v[164:167], v[204:207], v[68:71]
	v_mfma_f32_16x16x32_bf16 v[64:67], v[172:175], v[204:207], v[64:67]
	s_setprio 0
	s_barrier
	s_and_b32 s37, s18, 0xffff
	s_mov_b32 m0, s73
	s_mov_b32 s38, s6
	s_mov_b32 s39, s7
	s_add_u32 s4, s36, 0x4000
	ds_read_b128 v[176:179], v144 offset:16384
	ds_read_b128 v[180:183], v144 offset:17408
	ds_read_b128 v[184:187], v144 offset:18432
	ds_read_b128 v[188:191], v144 offset:19456
	ds_read_b128 v[192:195], v144 offset:20480
	ds_read_b128 v[196:199], v144 offset:21504
	ds_read_b128 v[200:203], v144 offset:22528
	ds_read_b128 v[204:207], v144 offset:23552
	buffer_load_dwordx4 v139, s[36:39], 0 offen lds
	s_mov_b32 m0, s74
	s_addc_u32 s5, s18, 0
	buffer_load_dwordx4 v141, s[36:39], 0 offen lds
	s_and_b32 s5, s5, 0xffff
	s_mov_b32 m0, s75
	s_and_b32 s41, s19, 0xffff
	buffer_load_dwordx4 v139, s[4:7], 0 offen lds
	s_mov_b32 m0, s76
	s_mov_b32 s42, s6
	buffer_load_dwordx4 v141, s[4:7], 0 offen lds
	s_mov_b32 s43, s7
	s_mov_b32 m0, s61
	s_nop 0
	buffer_load_dwordx4 v138, s[40:43], 0 offen lds
	s_mov_b32 m0, s77
	s_nop 0
	buffer_load_dwordx4 v140, s[40:43], 0 offen lds
	s_waitcnt vmcnt(8)
	s_waitcnt lgkmcnt(0)
	s_barrier
	s_setprio 1
	v_mfma_f32_16x16x32_bf16 v[60:63], v[132:135], v[176:179], v[60:63]
	v_mfma_f32_16x16x32_bf16 v[56:59], v[152:155], v[176:179], v[56:59]
	v_mfma_f32_16x16x32_bf16 v[44:47], v[132:135], v[184:187], v[44:47]
	v_mfma_f32_16x16x32_bf16 v[40:43], v[152:155], v[184:187], v[40:43]
	v_mfma_f32_16x16x32_bf16 v[28:31], v[132:135], v[192:195], v[28:31]
	v_mfma_f32_16x16x32_bf16 v[24:27], v[152:155], v[192:195], v[24:27]
	v_mfma_f32_16x16x32_bf16 v[12:15], v[132:135], v[200:203], v[12:15]
	v_mfma_f32_16x16x32_bf16 v[8:11], v[152:155], v[200:203], v[8:11]
	v_mfma_f32_16x16x32_bf16 v[60:63], v[148:151], v[180:183], v[60:63]
	v_mfma_f32_16x16x32_bf16 v[56:59], v[156:159], v[180:183], v[56:59]
	v_mfma_f32_16x16x32_bf16 v[44:47], v[148:151], v[188:191], v[44:47]
	v_mfma_f32_16x16x32_bf16 v[40:43], v[156:159], v[188:191], v[40:43]
	v_mfma_f32_16x16x32_bf16 v[28:31], v[148:151], v[196:199], v[28:31]
	v_mfma_f32_16x16x32_bf16 v[24:27], v[156:159], v[196:199], v[24:27]
	v_mfma_f32_16x16x32_bf16 v[12:15], v[148:151], v[204:207], v[12:15]
	v_mfma_f32_16x16x32_bf16 v[8:11], v[156:159], v[204:207], v[8:11]
	v_mfma_f32_16x16x32_bf16 v[52:55], v[160:163], v[176:179], v[52:55]
	v_mfma_f32_16x16x32_bf16 v[48:51], v[168:171], v[176:179], v[48:51]
	v_mfma_f32_16x16x32_bf16 v[36:39], v[160:163], v[184:187], v[36:39]
	v_mfma_f32_16x16x32_bf16 v[32:35], v[168:171], v[184:187], v[32:35]
	v_mfma_f32_16x16x32_bf16 v[20:23], v[160:163], v[192:195], v[20:23]
	v_mfma_f32_16x16x32_bf16 v[16:19], v[168:171], v[192:195], v[16:19]
	v_mfma_f32_16x16x32_bf16 v[4:7], v[160:163], v[200:203], v[4:7]
	v_mfma_f32_16x16x32_bf16 v[0:3], v[168:171], v[200:203], v[0:3]
	v_mfma_f32_16x16x32_bf16 v[52:55], v[164:167], v[180:183], v[52:55]
	v_mfma_f32_16x16x32_bf16 v[48:51], v[172:175], v[180:183], v[48:51]
	v_mfma_f32_16x16x32_bf16 v[36:39], v[164:167], v[188:191], v[36:39]
	v_mfma_f32_16x16x32_bf16 v[32:35], v[172:175], v[188:191], v[32:35]
	v_mfma_f32_16x16x32_bf16 v[20:23], v[164:167], v[196:199], v[20:23]
	v_mfma_f32_16x16x32_bf16 v[16:19], v[172:175], v[196:199], v[16:19]
	v_mfma_f32_16x16x32_bf16 v[4:7], v[164:167], v[204:207], v[4:7]
	v_mfma_f32_16x16x32_bf16 v[0:3], v[172:175], v[204:207], v[0:3]
	s_setprio 0
	s_barrier
; #define PG8_STAGE(bufoff, gbase, voff) do { const __amdgpu_buffer_rsrc_t _rs = __builtin_amdgcn_make_buffer_rsrc((void*)(gbase), 0, 0x7fffffff, 0x00020000); _Pragma("unroll") for (int _i = 0; _i < 2; ++_i) \
;         __builtin_amdgcn_raw_ptr_buffer_load_lds(_rs, (LAS unsigned*)(lds + (bufoff) + ldsw + _i * 8192), 16, (int)(voff)[_i], 0, 0, 0); } while (0)
; #define PG8_WAIT_V(n) asm volatile("s_waitcnt vmcnt(" #n ")" ::: "memory")
; #define PG8_WAIT_L(n) asm volatile("s_waitcnt lgkmcnt(" #n ")" ::: "memory")
; #define PG8_BAR __builtin_amdgcn_s_barrier()
; #define PG8_SCHED __builtin_amdgcn_sched_barrier(0)
; template <class Epi, class Sched, bool F8 = false>
; __device__ __forceinline__ void gemm_phase(LAS unsigned char* lds, const int lda, const int ldb, const Sched& S, const Epi& E) {
;     ...
;             PG8_LDB(B0, 1, 0); PG8_LDB(B1, 1, 1); PG8_SCHED; PG8_LDA(At, 1, 0); PG8_STAGE(PG8_SA(0, 1), a2 + hstepA, voffA);
;             PG8_WAIT_V(8); PG8_WAIT_L(0); PG8_BAR; PG8_MMA(0, 0, At, B0); PG8_MMA(0, 1, At, B1); PG8_BAR; PG8_SCHED;
;             PG8_LDA(At, 1, 1); PG8_STAGE(PG8_SB(1, 0), b3, voffB); PG8_STAGE(PG8_SB(1, 1), b3 + hstepB, voffB); PG8_STAGE(PG8_SA(1, 0), a3, voffA);
;             PG8_WAIT_V(8); PG8_WAIT_L(0); PG8_BAR; PG8_MMA(1, 0, At, B0); PG8_MMA(1, 1, At, B1); PG8_BAR; PG8_SCHED;
	ds_read_b128 v[132:135], v145
	ds_read_b128 v[148:151], v145 offset:1024
	ds_read_b128 v[152:155], v145 offset:2048
	ds_read_b128 v[156:159], v145 offset:3072
	ds_read_b128 v[160:163], v146
	ds_read_b128 v[164:167], v146 offset:1024
	ds_read_b128 v[168:171], v146 offset:2048
	ds_read_b128 v[172:175], v146 offset:3072
	s_add_u32 s4, s40, 0x100000
	s_addc_u32 s5, s19, 0
	s_and_b32 s5, s5, 0xffff
	s_mov_b32 m0, s78
	ds_read_b128 v[176:179], v144 offset:32768
	ds_read_b128 v[180:183], v144 offset:33792
	ds_read_b128 v[184:187], v144 offset:34816
	ds_read_b128 v[188:191], v144 offset:35840
	ds_read_b128 v[192:195], v144 offset:36864
	ds_read_b128 v[196:199], v144 offset:37888
	ds_read_b128 v[200:203], v144 offset:38912
	ds_read_b128 v[204:207], v144 offset:39936
	buffer_load_dwordx4 v138, s[4:7], 0 offen lds
	s_mov_b32 m0, s79
	s_nop 0
	buffer_load_dwordx4 v140, s[4:7], 0 offen lds
	s_waitcnt vmcnt(8)
	s_waitcnt lgkmcnt(0)
	s_barrier
	s_setprio 1
	v_mfma_f32_16x16x32_bf16 v[124:127], v[132:135], v[176:179], v[124:127]
	v_mfma_f32_16x16x32_bf16 v[120:123], v[152:155], v[176:179], v[120:123]
	v_mfma_f32_16x16x32_bf16 v[108:111], v[132:135], v[184:187], v[108:111]
	v_mfma_f32_16x16x32_bf16 v[104:107], v[152:155], v[184:187], v[104:107]
	v_mfma_f32_16x16x32_bf16 v[92:95], v[132:135], v[192:195], v[92:95]
	v_mfma_f32_16x16x32_bf16 v[88:91], v[152:155], v[192:195], v[88:91]
	v_mfma_f32_16x16x32_bf16 v[76:79], v[132:135], v[200:203], v[76:79]
	v_mfma_f32_16x16x32_bf16 v[72:75], v[152:155], v[200:203], v[72:75]
	v_mfma_f32_16x16x32_bf16 v[124:127], v[148:151], v[180:183], v[124:127]
	v_mfma_f32_16x16x32_bf16 v[120:123], v[156:159], v[180:183], v[120:123]
	v_mfma_f32_16x16x32_bf16 v[108:111], v[148:151], v[188:191], v[108:111]
	v_mfma_f32_16x16x32_bf16 v[104:107], v[156:159], v[188:191], v[104:107]
	v_mfma_f32_16x16x32_bf16 v[92:95], v[148:151], v[196:199], v[92:95]
	v_mfma_f32_16x16x32_bf16 v[88:91], v[156:159], v[196:199], v[88:91]
	v_mfma_f32_16x16x32_bf16 v[76:79], v[148:151], v[204:207], v[76:79]
	v_mfma_f32_16x16x32_bf16 v[72:75], v[156:159], v[204:207], v[72:75]
	v_mfma_f32_16x16x32_bf16 v[116:119], v[160:163], v[176:179], v[116:119]
	v_mfma_f32_16x16x32_bf16 v[112:115], v[168:171], v[176:179], v[112:115]
	v_mfma_f32_16x16x32_bf16 v[100:103], v[160:163], v[184:187], v[100:103]
	v_mfma_f32_16x16x32_bf16 v[96:99], v[168:171], v[184:187], v[96:99]
	v_mfma_f32_16x16x32_bf16 v[84:87], v[160:163], v[192:195], v[84:87]
	v_mfma_f32_16x16x32_bf16 v[80:83], v[168:171], v[192:195], v[80:83]
	v_mfma_f32_16x16x32_bf16 v[68:71], v[160:163], v[200:203], v[68:71]
	v_mfma_f32_16x16x32_bf16 v[64:67], v[168:171], v[200:203], v[64:67]
	v_mfma_f32_16x16x32_bf16 v[116:119], v[164:167], v[180:183], v[116:119]
	v_mfma_f32_16x16x32_bf16 v[112:115], v[172:175], v[180:183], v[112:115]
	v_mfma_f32_16x16x32_bf16 v[100:103], v[164:167], v[188:191], v[100:103]
	v_mfma_f32_16x16x32_bf16 v[96:99], v[172:175], v[188:191], v[96:99]
	v_mfma_f32_16x16x32_bf16 v[84:87], v[164:167], v[196:199], v[84:87]
	v_mfma_f32_16x16x32_bf16 v[80:83], v[172:175], v[196:199], v[80:83]
	v_mfma_f32_16x16x32_bf16 v[68:71], v[164:167], v[204:207], v[68:71]
	v_mfma_f32_16x16x32_bf16 v[64:67], v[172:175], v[204:207], v[64:67]
	s_setprio 0
	s_barrier
	s_add_u32 s4, s36, 0x8000
	s_addc_u32 s5, s18, 0
	s_mov_b32 m0, s86
	s_and_b32 s5, s5, 0xffff
	ds_read_b128 v[176:179], v144 offset:49152
	ds_read_b128 v[180:183], v144 offset:50176
	ds_read_b128 v[184:187], v144 offset:51200
	ds_read_b128 v[188:191], v144 offset:52224
	ds_read_b128 v[192:195], v144 offset:53248
	ds_read_b128 v[196:199], v144 offset:54272
	ds_read_b128 v[200:203], v144 offset:55296
	ds_read_b128 v[204:207], v144 offset:56320
	buffer_load_dwordx4 v139, s[4:7], 0 offen lds
	s_mov_b32 m0, s87
	s_mov_b32 s19, s7
	buffer_load_dwordx4 v141, s[4:7], 0 offen lds
	s_add_u32 s4, s36, 0xc000
	s_addc_u32 s5, s18, 0
	s_and_b32 s5, s5, 0xffff
	s_mov_b32 m0, s90
	s_and_b32 s17, s17, 0xffff
	buffer_load_dwordx4 v139, s[4:7], 0 offen lds
	s_mov_b32 m0, s91
	s_mov_b32 s18, s6
	buffer_load_dwordx4 v141, s[4:7], 0 offen lds
	s_mov_b32 m0, s88
	s_nop 0
	buffer_load_dwordx4 v138, s[16:19], 0 offen lds
	s_mov_b32 m0, s89
	s_nop 0
	buffer_load_dwordx4 v140, s[16:19], 0 offen lds
	s_waitcnt vmcnt(8)
	s_waitcnt lgkmcnt(0)
	s_barrier
	s_setprio 1
	v_mfma_f32_16x16x32_bf16 v[60:63], v[132:135], v[176:179], v[60:63]
	v_mfma_f32_16x16x32_bf16 v[56:59], v[152:155], v[176:179], v[56:59]
	v_mfma_f32_16x16x32_bf16 v[44:47], v[132:135], v[184:187], v[44:47]
	v_mfma_f32_16x16x32_bf16 v[40:43], v[152:155], v[184:187], v[40:43]
	v_mfma_f32_16x16x32_bf16 v[28:31], v[132:135], v[192:195], v[28:31]
	v_mfma_f32_16x16x32_bf16 v[24:27], v[152:155], v[192:195], v[24:27]
	v_mfma_f32_16x16x32_bf16 v[12:15], v[132:135], v[200:203], v[12:15]
	v_mfma_f32_16x16x32_bf16 v[8:11], v[152:155], v[200:203], v[8:11]
	v_mfma_f32_16x16x32_bf16 v[60:63], v[148:151], v[180:183], v[60:63]
	v_mfma_f32_16x16x32_bf16 v[56:59], v[156:159], v[180:183], v[56:59]
	v_mfma_f32_16x16x32_bf16 v[44:47], v[148:151], v[188:191], v[44:47]
	v_mfma_f32_16x16x32_bf16 v[40:43], v[156:159], v[188:191], v[40:43]
	v_mfma_f32_16x16x32_bf16 v[28:31], v[148:151], v[196:199], v[28:31]
	v_mfma_f32_16x16x32_bf16 v[24:27], v[156:159], v[196:199], v[24:27]
	v_mfma_f32_16x16x32_bf16 v[12:15], v[148:151], v[204:207], v[12:15]
	v_mfma_f32_16x16x32_bf16 v[8:11], v[156:159], v[204:207], v[8:11]
	v_mfma_f32_16x16x32_bf16 v[52:55], v[160:163], v[176:179], v[52:55]
	v_mfma_f32_16x16x32_bf16 v[48:51], v[168:171], v[176:179], v[48:51]
	v_mfma_f32_16x16x32_bf16 v[36:39], v[160:163], v[184:187], v[36:39]
	v_mfma_f32_16x16x32_bf16 v[32:35], v[168:171], v[184:187], v[32:35]
	v_mfma_f32_16x16x32_bf16 v[20:23], v[160:163], v[192:195], v[20:23]
	v_mfma_f32_16x16x32_bf16 v[16:19], v[168:171], v[192:195], v[16:19]
	v_mfma_f32_16x16x32_bf16 v[4:7], v[160:163], v[200:203], v[4:7]
	v_mfma_f32_16x16x32_bf16 v[0:3], v[168:171], v[200:203], v[0:3]
	v_mfma_f32_16x16x32_bf16 v[52:55], v[164:167], v[180:183], v[52:55]
	v_mfma_f32_16x16x32_bf16 v[48:51], v[172:175], v[180:183], v[48:51]
	v_mfma_f32_16x16x32_bf16 v[36:39], v[164:167], v[188:191], v[36:39]
	v_mfma_f32_16x16x32_bf16 v[32:35], v[172:175], v[188:191], v[32:35]
	v_mfma_f32_16x16x32_bf16 v[20:23], v[164:167], v[196:199], v[20:23]
	v_mfma_f32_16x16x32_bf16 v[16:19], v[172:175], v[196:199], v[16:19]
	v_mfma_f32_16x16x32_bf16 v[4:7], v[164:167], v[204:207], v[4:7]
	v_mfma_f32_16x16x32_bf16 v[0:3], v[172:175], v[204:207], v[0:3]
	s_setprio 0
	s_barrier
	s_add_i32 s64, s64, 2
	s_add_u32 s51, s51, 0x10000
	s_addc_u32 s67, s67, 0
	s_add_u32 vcc_lo, vcc_lo, 0x100
	s_addc_u32 vcc_hi, vcc_hi, 0
	s_cmp_gt_u32 s64, 61
	s_cbranch_scc0 .LBB0_632
	s_and_b64 vcc, exec, s[26:27]
	s_cbranch_vccz .LBB0_635
	s_barrier

; #define PG8_STAGE(bufoff, gbase, voff) do { const __amdgpu_buffer_rsrc_t _rs = __builtin_amdgcn_make_buffer_rsrc((void*)(gbase), 0, 0x7fffffff, 0x00020000); _Pragma("unroll") for (int _i = 0; _i < 2; ++_i) \
;         __builtin_amdgcn_raw_ptr_buffer_load_lds(_rs, (LAS unsigned*)(lds + (bufoff) + ldsw + _i * 8192), 16, (int)(voff)[_i], 0, 0, 0); } while (0)
; #define PG8_WAIT_V(n) asm volatile("s_waitcnt vmcnt(" #n ")" ::: "memory")
; #define PG8_WAIT_L(n) asm volatile("s_waitcnt lgkmcnt(" #n ")" ::: "memory")
; #define PG8_BAR __builtin_amdgcn_s_barrier()
; #define PG8_SCHED __builtin_amdgcn_sched_barrier(0)
; template <class Epi, class Sched, bool F8 = false>
; __device__ __forceinline__ void gemm_phase(LAS unsigned char* lds, const int lda, const int ldb, const Sched& S, const Epi& E) {
;     ...
;             PG8_LDB(B0, 0, 0); PG8_LDB(B1, 0, 1); PG8_SCHED; PG8_LDA(At, 0, 0); PG8_STAGE(PG8_SA(1, 1), a1 + hstepA, voffA);
;             PG8_WAIT_V(8); PG8_WAIT_L(0); PG8_BAR; PG8_MMA(0, 0, At, B0); PG8_MMA(0, 1, At, B1); PG8_BAR; PG8_SCHED;
;             PG8_LDA(At, 0, 1); PG8_STAGE(PG8_SB(0, 0), b2, voffB); PG8_STAGE(PG8_SB(0, 1), b2 + hstepB, voffB); PG8_STAGE(PG8_SA(0, 0), a2, voffA);
;             PG8_WAIT_V(8); PG8_WAIT_L(0); PG8_BAR; PG8_MMA(1, 0, At, B0); PG8_MMA(1, 1, At, B1); PG8_BAR; PG8_SCHED;
.LBB0_778:
	ds_read_b128 v[118:121], v194
	ds_read_b128 v[122:125], v194 offset:1024
	ds_read_b128 v[130:133], v194 offset:2048
	ds_read_b128 v[134:137], v194 offset:3072
	ds_read_b128 v[138:141], v195
	ds_read_b128 v[142:145], v195 offset:1024
	ds_read_b128 v[146:149], v195 offset:2048
	ds_read_b128 v[150:153], v195 offset:3072
	s_add_u32 s4, s33, 0xfff00080
	s_addc_u32 s5, s43, -1
	s_cmp_eq_u32 s45, 60
	s_cselect_b32 s20, s46, s4
	s_cselect_b32 s7, s47, s5
	s_cselect_b32 s6, s49, s9
	s_cselect_b32 s16, s48, s8
	s_add_u32 s4, s20, 0x80
	s_addc_u32 s5, s7, 0
	s_and_b32 s13, s43, 0xffff
	s_mov_b32 s12, s33
	s_mov_b32 m0, s84
	ds_read_b128 v[162:165], v196
	ds_read_b128 v[166:169], v196 offset:1024
	ds_read_b128 v[170:173], v196 offset:2048
	ds_read_b128 v[186:189], v196 offset:3072
	ds_read_b128 v[200:203], v196 offset:4096
	ds_read_b128 v[204:207], v196 offset:5120
	ds_read_b128 v[208:211], v196 offset:6144
	ds_read_b128 v[212:215], v196 offset:7168
	buffer_load_dwordx4 v175, s[12:15], 0 offen lds
	s_mov_b32 m0, s86
	s_nop 0
	buffer_load_dwordx4 v179, s[12:15], 0 offen lds
	s_waitcnt vmcnt(8)
	s_waitcnt lgkmcnt(0)
	s_barrier
	s_setprio 1
	v_mfma_f32_16x16x32_bf16 v[158:161], v[118:121], v[162:165], v[158:161]
	v_mfma_f32_16x16x32_bf16 v[60:63], v[130:133], v[162:165], v[60:63]
	v_mfma_f32_16x16x32_bf16 v[154:157], v[118:121], v[170:173], v[154:157]
	v_mfma_f32_16x16x32_bf16 v[52:55], v[130:133], v[170:173], v[52:55]
	v_mfma_f32_16x16x32_bf16 v[114:117], v[118:121], v[200:203], v[114:117]
	v_mfma_f32_16x16x32_bf16 v[44:47], v[130:133], v[200:203], v[44:47]
	v_mfma_f32_16x16x32_bf16 v[108:111], v[118:121], v[208:211], v[110:113]
	v_mfma_f32_16x16x32_bf16 v[36:39], v[130:133], v[208:211], v[36:39]
	v_mfma_f32_16x16x32_bf16 v[158:161], v[122:125], v[166:169], v[158:161]
	v_mfma_f32_16x16x32_bf16 v[60:63], v[134:137], v[166:169], v[60:63]
	v_mfma_f32_16x16x32_bf16 v[154:157], v[122:125], v[186:189], v[154:157]
	v_mfma_f32_16x16x32_bf16 v[52:55], v[134:137], v[186:189], v[52:55]
	v_mfma_f32_16x16x32_bf16 v[114:117], v[122:125], v[204:207], v[114:117]
	v_mfma_f32_16x16x32_bf16 v[44:47], v[134:137], v[204:207], v[44:47]
	v_mfma_f32_16x16x32_bf16 v[108:111], v[122:125], v[212:215], v[108:111]
	v_mfma_f32_16x16x32_bf16 v[36:39], v[134:137], v[212:215], v[36:39]
	v_mfma_f32_16x16x32_bf16 v[104:107], v[138:141], v[162:165], v[104:107]
	v_mfma_f32_16x16x32_bf16 v[56:59], v[146:149], v[162:165], v[56:59]
	v_mfma_f32_16x16x32_bf16 v[126:129], v[138:141], v[170:173], v[126:129]
	v_mfma_f32_16x16x32_bf16 v[48:51], v[146:149], v[170:173], v[48:51]
	v_mfma_f32_16x16x32_bf16 v[100:103], v[138:141], v[200:203], v[100:103]
	v_mfma_f32_16x16x32_bf16 v[40:43], v[146:149], v[200:203], v[40:43]
	v_mfma_f32_16x16x32_bf16 v[96:99], v[138:141], v[208:211], v[96:99]
	v_mfma_f32_16x16x32_bf16 v[32:35], v[146:149], v[208:211], v[32:35]
	v_mfma_f32_16x16x32_bf16 v[104:107], v[142:145], v[166:169], v[104:107]
	v_mfma_f32_16x16x32_bf16 v[56:59], v[150:153], v[166:169], v[56:59]
	v_mfma_f32_16x16x32_bf16 v[126:129], v[142:145], v[186:189], v[126:129]
	v_mfma_f32_16x16x32_bf16 v[48:51], v[150:153], v[186:189], v[48:51]
	v_mfma_f32_16x16x32_bf16 v[100:103], v[142:145], v[204:207], v[100:103]
	v_mfma_f32_16x16x32_bf16 v[40:43], v[150:153], v[204:207], v[40:43]
	v_mfma_f32_16x16x32_bf16 v[96:99], v[142:145], v[212:215], v[96:99]
	v_mfma_f32_16x16x32_bf16 v[32:35], v[150:153], v[212:215], v[32:35]
	s_setprio 0
	s_barrier
	s_and_b32 s17, s6, 0xffff
	s_mov_b32 m0, s68
	s_mov_b32 s18, s14
	s_mov_b32 s19, s15
	s_add_u32 s12, s16, 0x4000
	ds_read_b128 v[162:165], v196 offset:16384
	ds_read_b128 v[166:169], v196 offset:17408
	ds_read_b128 v[170:173], v196 offset:18432
	ds_read_b128 v[186:189], v196 offset:19456
	ds_read_b128 v[200:203], v196 offset:20480
	ds_read_b128 v[204:207], v196 offset:21504
	ds_read_b128 v[208:211], v196 offset:22528
	ds_read_b128 v[212:215], v196 offset:23552
	buffer_load_dwordx4 v177, s[16:19], 0 offen lds
	s_mov_b32 m0, s69
	s_addc_u32 s13, s6, 0
	buffer_load_dwordx4 v193, s[16:19], 0 offen lds
	s_and_b32 s13, s13, 0xffff
	s_mov_b32 m0, s70
	s_and_b32 s21, s7, 0xffff
	buffer_load_dwordx4 v177, s[12:15], 0 offen lds
	s_mov_b32 m0, s71
	s_mov_b32 s22, s14
	buffer_load_dwordx4 v193, s[12:15], 0 offen lds
	s_mov_b32 s23, s15
	s_mov_b32 m0, s51
	s_nop 0
	buffer_load_dwordx4 v175, s[20:23], 0 offen lds
	s_mov_b32 m0, s72
	s_nop 0
	buffer_load_dwordx4 v179, s[20:23], 0 offen lds
	s_waitcnt vmcnt(8)
	s_waitcnt lgkmcnt(0)
	s_barrier
	s_setprio 1
	v_mfma_f32_16x16x32_bf16 v[92:95], v[118:121], v[162:165], v[92:95]
	v_mfma_f32_16x16x32_bf16 v[28:31], v[130:133], v[162:165], v[28:31]
	v_mfma_f32_16x16x32_bf16 v[84:87], v[118:121], v[170:173], v[84:87]
	v_mfma_f32_16x16x32_bf16 v[20:23], v[130:133], v[170:173], v[20:23]
	v_mfma_f32_16x16x32_bf16 v[76:79], v[118:121], v[200:203], v[76:79]
	v_mfma_f32_16x16x32_bf16 v[12:15], v[130:133], v[200:203], v[12:15]
	v_mfma_f32_16x16x32_bf16 v[72:75], v[118:121], v[208:211], v[72:75]
	v_mfma_f32_16x16x32_bf16 v[4:7], v[130:133], v[208:211], v[4:7]
	v_mfma_f32_16x16x32_bf16 v[92:95], v[122:125], v[166:169], v[92:95]
	v_mfma_f32_16x16x32_bf16 v[28:31], v[134:137], v[166:169], v[28:31]
	v_mfma_f32_16x16x32_bf16 v[84:87], v[122:125], v[186:189], v[84:87]
	v_mfma_f32_16x16x32_bf16 v[20:23], v[134:137], v[186:189], v[20:23]
	v_mfma_f32_16x16x32_bf16 v[76:79], v[122:125], v[204:207], v[76:79]
	v_mfma_f32_16x16x32_bf16 v[12:15], v[134:137], v[204:207], v[12:15]
	v_mfma_f32_16x16x32_bf16 v[72:75], v[122:125], v[212:215], v[72:75]
	v_mfma_f32_16x16x32_bf16 v[4:7], v[134:137], v[212:215], v[4:7]
	v_mfma_f32_16x16x32_bf16 v[88:91], v[138:141], v[162:165], v[88:91]
	v_mfma_f32_16x16x32_bf16 v[24:27], v[146:149], v[162:165], v[24:27]
	v_mfma_f32_16x16x32_bf16 v[80:83], v[138:141], v[170:173], v[80:83]
	v_mfma_f32_16x16x32_bf16 v[16:19], v[146:149], v[170:173], v[16:19]
	v_mfma_f32_16x16x32_bf16 v[68:71], v[138:141], v[200:203], v[68:71]
	v_mfma_f32_16x16x32_bf16 v[8:11], v[146:149], v[200:203], v[8:11]
	v_mfma_f32_16x16x32_bf16 v[64:67], v[138:141], v[208:211], v[64:67]
	v_mfma_f32_16x16x32_bf16 v[0:3], v[146:149], v[208:211], v[0:3]
	v_mfma_f32_16x16x32_bf16 v[88:91], v[142:145], v[166:169], v[88:91]
	v_mfma_f32_16x16x32_bf16 v[24:27], v[150:153], v[166:169], v[24:27]
	v_mfma_f32_16x16x32_bf16 v[80:83], v[142:145], v[186:189], v[80:83]
	v_mfma_f32_16x16x32_bf16 v[16:19], v[150:153], v[186:189], v[16:19]
	v_mfma_f32_16x16x32_bf16 v[68:71], v[142:145], v[204:207], v[68:71]
	v_mfma_f32_16x16x32_bf16 v[8:11], v[150:153], v[204:207], v[8:11]
	v_mfma_f32_16x16x32_bf16 v[64:67], v[142:145], v[212:215], v[64:67]
	v_mfma_f32_16x16x32_bf16 v[0:3], v[150:153], v[212:215], v[0:3]
	s_setprio 0
	s_barrier
; #define PG8_STAGE(bufoff, gbase, voff) do { const __amdgpu_buffer_rsrc_t _rs = __builtin_amdgcn_make_buffer_rsrc((void*)(gbase), 0, 0x7fffffff, 0x00020000); _Pragma("unroll") for (int _i = 0; _i < 2; ++_i) \
;         __builtin_amdgcn_raw_ptr_buffer_load_lds(_rs, (LAS unsigned*)(lds + (bufoff) + ldsw + _i * 8192), 16, (int)(voff)[_i], 0, 0, 0); } while (0)
; #define PG8_WAIT_V(n) asm volatile("s_waitcnt vmcnt(" #n ")" ::: "memory")
; #define PG8_WAIT_L(n) asm volatile("s_waitcnt lgkmcnt(" #n ")" ::: "memory")
; #define PG8_BAR __builtin_amdgcn_s_barrier()
; #define PG8_SCHED __builtin_amdgcn_sched_barrier(0)
; template <class Epi, class Sched, bool F8 = false>
; __device__ __forceinline__ void gemm_phase(LAS unsigned char* lds, const int lda, const int ldb, const Sched& S, const Epi& E) {
;     ...
;             PG8_LDB(B0, 1, 0); PG8_LDB(B1, 1, 1); PG8_SCHED; PG8_LDA(At, 1, 0); PG8_STAGE(PG8_SA(0, 1), a2 + hstepA, voffA);
;             PG8_WAIT_V(8); PG8_WAIT_L(0); PG8_BAR; PG8_MMA(0, 0, At, B0); PG8_MMA(0, 1, At, B1); PG8_BAR; PG8_SCHED;
;             PG8_LDA(At, 1, 1); PG8_STAGE(PG8_SB(1, 0), b3, voffB); PG8_STAGE(PG8_SB(1, 1), b3 + hstepB, voffB); PG8_STAGE(PG8_SA(1, 0), a3, voffA);
;             PG8_WAIT_V(8); PG8_WAIT_L(0); PG8_BAR; PG8_MMA(1, 0, At, B0); PG8_MMA(1, 1, At, B1); PG8_BAR; PG8_SCHED;
	ds_read_b128 v[118:121], v197
	ds_read_b128 v[122:125], v197 offset:1024
	ds_read_b128 v[130:133], v197 offset:2048
	ds_read_b128 v[134:137], v197 offset:3072
	ds_read_b128 v[138:141], v198
	ds_read_b128 v[142:145], v198 offset:1024
	ds_read_b128 v[146:149], v198 offset:2048
	ds_read_b128 v[150:153], v198 offset:3072
	s_add_u32 s12, s20, 0x100000
	s_addc_u32 s7, s7, 0
	s_and_b32 s13, s7, 0xffff
	s_mov_b32 m0, s73
	ds_read_b128 v[162:165], v196 offset:32768
	ds_read_b128 v[166:169], v196 offset:33792
	ds_read_b128 v[170:173], v196 offset:34816
	ds_read_b128 v[186:189], v196 offset:35840
	ds_read_b128 v[200:203], v196 offset:36864
	ds_read_b128 v[204:207], v196 offset:37888
	ds_read_b128 v[208:211], v196 offset:38912
	ds_read_b128 v[212:215], v196 offset:39936
	buffer_load_dwordx4 v175, s[12:15], 0 offen lds
	s_mov_b32 m0, s74
	s_nop 0
	buffer_load_dwordx4 v179, s[12:15], 0 offen lds
	s_waitcnt vmcnt(8)
	s_waitcnt lgkmcnt(0)
	s_barrier
	s_setprio 1
	v_mfma_f32_16x16x32_bf16 v[158:161], v[118:121], v[162:165], v[158:161]
	v_mfma_f32_16x16x32_bf16 v[60:63], v[130:133], v[162:165], v[60:63]
	v_mfma_f32_16x16x32_bf16 v[154:157], v[118:121], v[170:173], v[154:157]
	v_mfma_f32_16x16x32_bf16 v[52:55], v[130:133], v[170:173], v[52:55]
	v_mfma_f32_16x16x32_bf16 v[112:115], v[118:121], v[200:203], v[114:117]
	v_mfma_f32_16x16x32_bf16 v[44:47], v[130:133], v[200:203], v[44:47]
	v_mfma_f32_16x16x32_bf16 v[108:111], v[118:121], v[208:211], v[108:111]
	v_mfma_f32_16x16x32_bf16 v[36:39], v[130:133], v[208:211], v[36:39]
	v_mfma_f32_16x16x32_bf16 v[158:161], v[122:125], v[166:169], v[158:161]
	v_mfma_f32_16x16x32_bf16 v[60:63], v[134:137], v[166:169], v[60:63]
	v_mfma_f32_16x16x32_bf16 v[154:157], v[122:125], v[186:189], v[154:157]
	v_mfma_f32_16x16x32_bf16 v[52:55], v[134:137], v[186:189], v[52:55]
	v_mfma_f32_16x16x32_bf16 v[114:117], v[122:125], v[204:207], v[112:115]
	v_mfma_f32_16x16x32_bf16 v[44:47], v[134:137], v[204:207], v[44:47]
	v_mfma_f32_16x16x32_bf16 v[110:113], v[122:125], v[212:215], v[108:111]
	v_mfma_f32_16x16x32_bf16 v[36:39], v[134:137], v[212:215], v[36:39]
	v_mfma_f32_16x16x32_bf16 v[104:107], v[138:141], v[162:165], v[104:107]
	v_mfma_f32_16x16x32_bf16 v[56:59], v[146:149], v[162:165], v[56:59]
	v_mfma_f32_16x16x32_bf16 v[126:129], v[138:141], v[170:173], v[126:129]
	v_mfma_f32_16x16x32_bf16 v[48:51], v[146:149], v[170:173], v[48:51]
	v_mfma_f32_16x16x32_bf16 v[100:103], v[138:141], v[200:203], v[100:103]
	v_mfma_f32_16x16x32_bf16 v[40:43], v[146:149], v[200:203], v[40:43]
	v_mfma_f32_16x16x32_bf16 v[96:99], v[138:141], v[208:211], v[96:99]
	v_mfma_f32_16x16x32_bf16 v[32:35], v[146:149], v[208:211], v[32:35]
	v_mfma_f32_16x16x32_bf16 v[104:107], v[142:145], v[166:169], v[104:107]
	v_mfma_f32_16x16x32_bf16 v[56:59], v[150:153], v[166:169], v[56:59]
	v_mfma_f32_16x16x32_bf16 v[126:129], v[142:145], v[186:189], v[126:129]
	v_mfma_f32_16x16x32_bf16 v[48:51], v[150:153], v[186:189], v[48:51]
	v_mfma_f32_16x16x32_bf16 v[100:103], v[142:145], v[204:207], v[100:103]
	v_mfma_f32_16x16x32_bf16 v[40:43], v[150:153], v[204:207], v[40:43]
	v_mfma_f32_16x16x32_bf16 v[96:99], v[142:145], v[212:215], v[96:99]
	v_mfma_f32_16x16x32_bf16 v[32:35], v[150:153], v[212:215], v[32:35]
	s_setprio 0
	s_barrier
	s_add_u32 s12, s16, 0x8000
	s_addc_u32 s7, s6, 0
	s_mov_b32 m0, s78
	s_and_b32 s13, s7, 0xffff
	ds_read_b128 v[162:165], v196 offset:49152
	ds_read_b128 v[166:169], v196 offset:50176
	ds_read_b128 v[170:173], v196 offset:51200
	ds_read_b128 v[186:189], v196 offset:52224
	ds_read_b128 v[200:203], v196 offset:53248
	ds_read_b128 v[204:207], v196 offset:54272
	ds_read_b128 v[208:211], v196 offset:55296
	ds_read_b128 v[212:215], v196 offset:56320
	buffer_load_dwordx4 v177, s[12:15], 0 offen lds
	s_mov_b32 m0, s79
	s_mov_b32 s7, s15
	buffer_load_dwordx4 v193, s[12:15], 0 offen lds
	s_add_u32 s12, s16, 0xc000
	s_addc_u32 s6, s6, 0
	s_and_b32 s13, s6, 0xffff
	s_mov_b32 m0, s82
	s_and_b32 s5, s5, 0xffff
	buffer_load_dwordx4 v177, s[12:15], 0 offen lds
	s_mov_b32 m0, s83
	s_mov_b32 s6, s14
	buffer_load_dwordx4 v193, s[12:15], 0 offen lds
	s_mov_b32 m0, s80
	s_nop 0
	buffer_load_dwordx4 v175, s[4:7], 0 offen lds
	s_mov_b32 m0, s81
	s_nop 0
	buffer_load_dwordx4 v179, s[4:7], 0 offen lds
	s_waitcnt vmcnt(8)
	s_waitcnt lgkmcnt(0)
	s_barrier
	s_setprio 1
	v_mfma_f32_16x16x32_bf16 v[92:95], v[118:121], v[162:165], v[92:95]
	v_mfma_f32_16x16x32_bf16 v[28:31], v[130:133], v[162:165], v[28:31]
	v_mfma_f32_16x16x32_bf16 v[84:87], v[118:121], v[170:173], v[84:87]
	v_mfma_f32_16x16x32_bf16 v[20:23], v[130:133], v[170:173], v[20:23]
	v_mfma_f32_16x16x32_bf16 v[76:79], v[118:121], v[200:203], v[76:79]
	v_mfma_f32_16x16x32_bf16 v[12:15], v[130:133], v[200:203], v[12:15]
	v_mfma_f32_16x16x32_bf16 v[72:75], v[118:121], v[208:211], v[72:75]
	v_mfma_f32_16x16x32_bf16 v[4:7], v[130:133], v[208:211], v[4:7]
	v_mfma_f32_16x16x32_bf16 v[92:95], v[122:125], v[166:169], v[92:95]
	v_mfma_f32_16x16x32_bf16 v[28:31], v[134:137], v[166:169], v[28:31]
	v_mfma_f32_16x16x32_bf16 v[84:87], v[122:125], v[186:189], v[84:87]
	v_mfma_f32_16x16x32_bf16 v[20:23], v[134:137], v[186:189], v[20:23]
	v_mfma_f32_16x16x32_bf16 v[76:79], v[122:125], v[204:207], v[76:79]
	v_mfma_f32_16x16x32_bf16 v[12:15], v[134:137], v[204:207], v[12:15]
	v_mfma_f32_16x16x32_bf16 v[72:75], v[122:125], v[212:215], v[72:75]
	v_mfma_f32_16x16x32_bf16 v[4:7], v[134:137], v[212:215], v[4:7]
	v_mfma_f32_16x16x32_bf16 v[88:91], v[138:141], v[162:165], v[88:91]
	v_mfma_f32_16x16x32_bf16 v[24:27], v[146:149], v[162:165], v[24:27]
	v_mfma_f32_16x16x32_bf16 v[80:83], v[138:141], v[170:173], v[80:83]
	v_mfma_f32_16x16x32_bf16 v[16:19], v[146:149], v[170:173], v[16:19]
	v_mfma_f32_16x16x32_bf16 v[68:71], v[138:141], v[200:203], v[68:71]
	v_mfma_f32_16x16x32_bf16 v[8:11], v[146:149], v[200:203], v[8:11]
	v_mfma_f32_16x16x32_bf16 v[64:67], v[138:141], v[208:211], v[64:67]
	v_mfma_f32_16x16x32_bf16 v[0:3], v[146:149], v[208:211], v[0:3]
	v_mfma_f32_16x16x32_bf16 v[88:91], v[142:145], v[166:169], v[88:91]
	v_mfma_f32_16x16x32_bf16 v[24:27], v[150:153], v[166:169], v[24:27]
	v_mfma_f32_16x16x32_bf16 v[80:83], v[142:145], v[186:189], v[80:83]
	v_mfma_f32_16x16x32_bf16 v[16:19], v[150:153], v[186:189], v[16:19]
	v_mfma_f32_16x16x32_bf16 v[68:71], v[142:145], v[204:207], v[68:71]
	v_mfma_f32_16x16x32_bf16 v[8:11], v[150:153], v[204:207], v[8:11]
	v_mfma_f32_16x16x32_bf16 v[64:67], v[142:145], v[212:215], v[64:67]
	v_mfma_f32_16x16x32_bf16 v[0:3], v[150:153], v[212:215], v[0:3]
	s_setprio 0
	s_barrier
	s_add_i32 s45, s45, 2
	s_add_u32 s8, s8, 0x10000
	s_addc_u32 s9, s9, 0
	s_add_u32 s33, s33, 0x100
	s_addc_u32 s43, s43, 0
	s_cmp_gt_u32 s45, 61
	s_cbranch_scc0 .LBB0_778
	s_and_b64 vcc, exec, s[40:41]
	s_cbranch_vccz .LBB0_781
	s_barrier

; #define PG8_STAGE(bufoff, gbase, voff) do { const __amdgpu_buffer_rsrc_t _rs = __builtin_amdgcn_make_buffer_rsrc((void*)(gbase), 0, 0x7fffffff, 0x00020000); _Pragma("unroll") for (int _i = 0; _i < 2; ++_i) \
;         __builtin_amdgcn_raw_ptr_buffer_load_lds(_rs, (LAS unsigned*)(lds + (bufoff) + ldsw + _i * 8192), 16, (int)(voff)[_i], 0, 0, 0); } while (0)
; #define PG8_WAIT_V(n) asm volatile("s_waitcnt vmcnt(" #n ")" ::: "memory")
; #define PG8_WAIT_L(n) asm volatile("s_waitcnt lgkmcnt(" #n ")" ::: "memory")
; #define PG8_BAR __builtin_amdgcn_s_barrier()
; #define PG8_SCHED __builtin_amdgcn_sched_barrier(0)
; template <class Epi, class Sched, bool F8 = false>
; __device__ __forceinline__ void gemm_phase(LAS unsigned char* lds, const int lda, const int ldb, const Sched& S, const Epi& E) {
;     ...
;             PG8_LDB(B0, 0, 0); PG8_LDB(B1, 0, 1); PG8_SCHED; PG8_LDA(At, 0, 0); PG8_STAGE(PG8_SA(1, 1), a1 + hstepA, voffA);
;             PG8_WAIT_V(8); PG8_WAIT_L(0); PG8_BAR; PG8_MMA(0, 0, At, B0); PG8_MMA(0, 1, At, B1); PG8_BAR; PG8_SCHED;
;             PG8_LDA(At, 0, 1); PG8_STAGE(PG8_SB(0, 0), b2, voffB); PG8_STAGE(PG8_SB(0, 1), b2 + hstepB, voffB); PG8_STAGE(PG8_SA(0, 0), a2, voffA);
;             PG8_WAIT_V(8); PG8_WAIT_L(0); PG8_BAR; PG8_MMA(1, 0, At, B0); PG8_MMA(1, 1, At, B1); PG8_BAR; PG8_SCHED;
.LBB0_935:
	ds_read_b128 v[136:139], v142
	ds_read_b128 v[148:151], v142 offset:1024
	ds_read_b128 v[152:155], v142 offset:2048
	ds_read_b128 v[156:159], v142 offset:3072
	ds_read_b128 v[160:163], v143
	ds_read_b128 v[164:167], v143 offset:1024
	ds_read_b128 v[168:171], v143 offset:2048
	ds_read_b128 v[180:183], v143 offset:3072
	s_add_u32 s4, s91, 0xffd50080
	s_addc_u32 s5, s92, -1
	s_cmpk_eq_i32 s64, 0xa8
	s_cselect_b32 s20, s44, s4
	s_cselect_b32 s15, s45, s5
	s_cselect_b32 s14, s47, s90
	s_cselect_b32 s16, s46, s89
	s_add_u32 s12, s20, 0x80
	s_addc_u32 s13, s15, 0
	s_and_b32 s5, s92, 0xffff
	s_mov_b32 s4, s91
	s_mov_b32 m0, s79
	ds_read_b128 v[184:187], v144
	ds_read_b128 v[188:191], v144 offset:1024
	ds_read_b128 v[194:197], v144 offset:2048
	ds_read_b128 v[198:201], v144 offset:3072
	ds_read_b128 v[202:205], v144 offset:4096
	ds_read_b128 v[206:209], v144 offset:5120
	ds_read_b128 v[210:213], v144 offset:6144
	ds_read_b128 v[214:217], v144 offset:7168
	buffer_load_dwordx4 v128, s[4:7], 0 offen lds
	s_mov_b32 m0, s80
	s_nop 0
	buffer_load_dwordx4 v130, s[4:7], 0 offen lds
	s_waitcnt vmcnt(8)
	s_waitcnt lgkmcnt(0)
	s_barrier
	s_setprio 1
	v_mfma_f32_16x16x32_bf16 v[124:127], v[136:139], v[184:187], v[124:127]
	v_mfma_f32_16x16x32_bf16 v[120:123], v[152:155], v[184:187], v[120:123]
	v_mfma_f32_16x16x32_bf16 v[108:111], v[136:139], v[194:197], v[108:111]
	v_mfma_f32_16x16x32_bf16 v[104:107], v[152:155], v[194:197], v[104:107]
	v_mfma_f32_16x16x32_bf16 v[92:95], v[136:139], v[202:205], v[92:95]
	v_mfma_f32_16x16x32_bf16 v[88:91], v[152:155], v[202:205], v[88:91]
	v_mfma_f32_16x16x32_bf16 v[76:79], v[136:139], v[210:213], v[76:79]
	v_mfma_f32_16x16x32_bf16 v[72:75], v[152:155], v[210:213], v[72:75]
	v_mfma_f32_16x16x32_bf16 v[124:127], v[148:151], v[188:191], v[124:127]
	v_mfma_f32_16x16x32_bf16 v[120:123], v[156:159], v[188:191], v[120:123]
	v_mfma_f32_16x16x32_bf16 v[108:111], v[148:151], v[198:201], v[108:111]
	v_mfma_f32_16x16x32_bf16 v[104:107], v[156:159], v[198:201], v[104:107]
	v_mfma_f32_16x16x32_bf16 v[92:95], v[148:151], v[206:209], v[92:95]
	v_mfma_f32_16x16x32_bf16 v[88:91], v[156:159], v[206:209], v[88:91]
	v_mfma_f32_16x16x32_bf16 v[76:79], v[148:151], v[214:217], v[76:79]
	v_mfma_f32_16x16x32_bf16 v[72:75], v[156:159], v[214:217], v[72:75]
	v_mfma_f32_16x16x32_bf16 v[116:119], v[160:163], v[184:187], v[116:119]
	v_mfma_f32_16x16x32_bf16 v[112:115], v[168:171], v[184:187], v[112:115]
	v_mfma_f32_16x16x32_bf16 v[100:103], v[160:163], v[194:197], v[100:103]
	v_mfma_f32_16x16x32_bf16 v[96:99], v[168:171], v[194:197], v[96:99]
	v_mfma_f32_16x16x32_bf16 v[84:87], v[160:163], v[202:205], v[84:87]
	v_mfma_f32_16x16x32_bf16 v[80:83], v[168:171], v[202:205], v[80:83]
	v_mfma_f32_16x16x32_bf16 v[68:71], v[160:163], v[210:213], v[68:71]
	v_mfma_f32_16x16x32_bf16 v[64:67], v[168:171], v[210:213], v[64:67]
	v_mfma_f32_16x16x32_bf16 v[116:119], v[164:167], v[188:191], v[116:119]
	v_mfma_f32_16x16x32_bf16 v[112:115], v[180:183], v[188:191], v[112:115]
	v_mfma_f32_16x16x32_bf16 v[100:103], v[164:167], v[198:201], v[100:103]
	v_mfma_f32_16x16x32_bf16 v[96:99], v[180:183], v[198:201], v[96:99]
	v_mfma_f32_16x16x32_bf16 v[84:87], v[164:167], v[206:209], v[84:87]
	v_mfma_f32_16x16x32_bf16 v[80:83], v[180:183], v[206:209], v[80:83]
	v_mfma_f32_16x16x32_bf16 v[68:71], v[164:167], v[214:217], v[68:71]
	v_mfma_f32_16x16x32_bf16 v[64:67], v[180:183], v[214:217], v[64:67]
	s_setprio 0
	s_barrier
	s_and_b32 s17, s14, 0xffff
	s_mov_b32 m0, s49
	s_mov_b32 s18, s6
	s_mov_b32 s19, s7
	s_add_u32 s4, s16, 0x4000
	ds_read_b128 v[184:187], v144 offset:16384
	ds_read_b128 v[188:191], v144 offset:17408
	ds_read_b128 v[194:197], v144 offset:18432
	ds_read_b128 v[198:201], v144 offset:19456
	ds_read_b128 v[202:205], v144 offset:20480
	ds_read_b128 v[206:209], v144 offset:21504
	ds_read_b128 v[210:213], v144 offset:22528
	ds_read_b128 v[214:217], v144 offset:23552
	buffer_load_dwordx4 v129, s[16:19], 0 offen lds
	s_mov_b32 m0, s50
	s_addc_u32 s5, s14, 0
	buffer_load_dwordx4 v131, s[16:19], 0 offen lds
	s_and_b32 s5, s5, 0xffff
	s_mov_b32 m0, s51
	s_and_b32 s21, s15, 0xffff
	buffer_load_dwordx4 v129, s[4:7], 0 offen lds
	s_mov_b32 m0, s52
	s_mov_b32 s22, s6
	buffer_load_dwordx4 v131, s[4:7], 0 offen lds
	s_mov_b32 s23, s7
	s_mov_b32 m0, s48
	s_nop 0
	buffer_load_dwordx4 v128, s[20:23], 0 offen lds
	s_mov_b32 m0, s53
	s_nop 0
	buffer_load_dwordx4 v130, s[20:23], 0 offen lds
	s_waitcnt vmcnt(8)
	s_waitcnt lgkmcnt(0)
	s_barrier
	s_setprio 1
	v_mfma_f32_16x16x32_bf16 v[60:63], v[136:139], v[184:187], v[60:63]
	v_mfma_f32_16x16x32_bf16 v[56:59], v[152:155], v[184:187], v[56:59]
	v_mfma_f32_16x16x32_bf16 v[44:47], v[136:139], v[194:197], v[44:47]
	v_mfma_f32_16x16x32_bf16 v[40:43], v[152:155], v[194:197], v[40:43]
	v_mfma_f32_16x16x32_bf16 v[28:31], v[136:139], v[202:205], v[28:31]
	v_mfma_f32_16x16x32_bf16 v[24:27], v[152:155], v[202:205], v[24:27]
	v_mfma_f32_16x16x32_bf16 v[12:15], v[136:139], v[210:213], v[12:15]
	v_mfma_f32_16x16x32_bf16 v[8:11], v[152:155], v[210:213], v[8:11]
	v_mfma_f32_16x16x32_bf16 v[60:63], v[148:151], v[188:191], v[60:63]
	v_mfma_f32_16x16x32_bf16 v[56:59], v[156:159], v[188:191], v[56:59]
	v_mfma_f32_16x16x32_bf16 v[44:47], v[148:151], v[198:201], v[44:47]
	v_mfma_f32_16x16x32_bf16 v[40:43], v[156:159], v[198:201], v[40:43]
	v_mfma_f32_16x16x32_bf16 v[28:31], v[148:151], v[206:209], v[28:31]
	v_mfma_f32_16x16x32_bf16 v[24:27], v[156:159], v[206:209], v[24:27]
	v_mfma_f32_16x16x32_bf16 v[12:15], v[148:151], v[214:217], v[12:15]
	v_mfma_f32_16x16x32_bf16 v[8:11], v[156:159], v[214:217], v[8:11]
	v_mfma_f32_16x16x32_bf16 v[52:55], v[160:163], v[184:187], v[52:55]
	v_mfma_f32_16x16x32_bf16 v[48:51], v[168:171], v[184:187], v[48:51]
	v_mfma_f32_16x16x32_bf16 v[36:39], v[160:163], v[194:197], v[36:39]
	v_mfma_f32_16x16x32_bf16 v[32:35], v[168:171], v[194:197], v[32:35]
	v_mfma_f32_16x16x32_bf16 v[20:23], v[160:163], v[202:205], v[20:23]
	v_mfma_f32_16x16x32_bf16 v[16:19], v[168:171], v[202:205], v[16:19]
	v_mfma_f32_16x16x32_bf16 v[4:7], v[160:163], v[210:213], v[4:7]
	v_mfma_f32_16x16x32_bf16 v[0:3], v[168:171], v[210:213], v[0:3]
	v_mfma_f32_16x16x32_bf16 v[52:55], v[164:167], v[188:191], v[52:55]
	v_mfma_f32_16x16x32_bf16 v[48:51], v[180:183], v[188:191], v[48:51]
	v_mfma_f32_16x16x32_bf16 v[36:39], v[164:167], v[198:201], v[36:39]
	v_mfma_f32_16x16x32_bf16 v[32:35], v[180:183], v[198:201], v[32:35]
	v_mfma_f32_16x16x32_bf16 v[20:23], v[164:167], v[206:209], v[20:23]
	v_mfma_f32_16x16x32_bf16 v[16:19], v[180:183], v[206:209], v[16:19]
	v_mfma_f32_16x16x32_bf16 v[4:7], v[164:167], v[214:217], v[4:7]
	v_mfma_f32_16x16x32_bf16 v[0:3], v[180:183], v[214:217], v[0:3]
	s_setprio 0
	s_barrier
; #define PG8_STAGE(bufoff, gbase, voff) do { const __amdgpu_buffer_rsrc_t _rs = __builtin_amdgcn_make_buffer_rsrc((void*)(gbase), 0, 0x7fffffff, 0x00020000); _Pragma("unroll") for (int _i = 0; _i < 2; ++_i) \
;         __builtin_amdgcn_raw_ptr_buffer_load_lds(_rs, (LAS unsigned*)(lds + (bufoff) + ldsw + _i * 8192), 16, (int)(voff)[_i], 0, 0, 0); } while (0)
; #define PG8_WAIT_V(n) asm volatile("s_waitcnt vmcnt(" #n ")" ::: "memory")
; #define PG8_WAIT_L(n) asm volatile("s_waitcnt lgkmcnt(" #n ")" ::: "memory")
; #define PG8_BAR __builtin_amdgcn_s_barrier()
; #define PG8_SCHED __builtin_amdgcn_sched_barrier(0)
; template <class Epi, class Sched, bool F8 = false>
; __device__ __forceinline__ void gemm_phase(LAS unsigned char* lds, const int lda, const int ldb, const Sched& S, const Epi& E) {
;     ...
;             PG8_LDB(B0, 1, 0); PG8_LDB(B1, 1, 1); PG8_SCHED; PG8_LDA(At, 1, 0); PG8_STAGE(PG8_SA(0, 1), a2 + hstepA, voffA);
;             PG8_WAIT_V(8); PG8_WAIT_L(0); PG8_BAR; PG8_MMA(0, 0, At, B0); PG8_MMA(0, 1, At, B1); PG8_BAR; PG8_SCHED;
;             PG8_LDA(At, 1, 1); PG8_STAGE(PG8_SB(1, 0), b3, voffB); PG8_STAGE(PG8_SB(1, 1), b3 + hstepB, voffB); PG8_STAGE(PG8_SA(1, 0), a3, voffA);
;             PG8_WAIT_V(8); PG8_WAIT_L(0); PG8_BAR; PG8_MMA(1, 0, At, B0); PG8_MMA(1, 1, At, B1); PG8_BAR; PG8_SCHED;
	ds_read_b128 v[136:139], v145
	ds_read_b128 v[148:151], v145 offset:1024
	ds_read_b128 v[152:155], v145 offset:2048
	ds_read_b128 v[156:159], v145 offset:3072
	ds_read_b128 v[160:163], v146
	ds_read_b128 v[164:167], v146 offset:1024
	ds_read_b128 v[168:171], v146 offset:2048
	ds_read_b128 v[180:183], v146 offset:3072
	s_add_u32 s4, s20, 0x2b0000
	s_addc_u32 s5, s15, 0
	s_and_b32 s5, s5, 0xffff
	s_mov_b32 m0, s61
	ds_read_b128 v[184:187], v144 offset:32768
	ds_read_b128 v[188:191], v144 offset:33792
	ds_read_b128 v[194:197], v144 offset:34816
	ds_read_b128 v[198:201], v144 offset:35840
	ds_read_b128 v[202:205], v144 offset:36864
	ds_read_b128 v[206:209], v144 offset:37888
	ds_read_b128 v[210:213], v144 offset:38912
	ds_read_b128 v[214:217], v144 offset:39936
	buffer_load_dwordx4 v128, s[4:7], 0 offen lds
	s_mov_b32 m0, s66
	s_nop 0
	buffer_load_dwordx4 v130, s[4:7], 0 offen lds
	s_waitcnt vmcnt(8)
	s_waitcnt lgkmcnt(0)
	s_barrier
	s_setprio 1
	v_mfma_f32_16x16x32_bf16 v[124:127], v[136:139], v[184:187], v[124:127]
	v_mfma_f32_16x16x32_bf16 v[120:123], v[152:155], v[184:187], v[120:123]
	v_mfma_f32_16x16x32_bf16 v[108:111], v[136:139], v[194:197], v[108:111]
	v_mfma_f32_16x16x32_bf16 v[104:107], v[152:155], v[194:197], v[104:107]
	v_mfma_f32_16x16x32_bf16 v[92:95], v[136:139], v[202:205], v[92:95]
	v_mfma_f32_16x16x32_bf16 v[88:91], v[152:155], v[202:205], v[88:91]
	v_mfma_f32_16x16x32_bf16 v[76:79], v[136:139], v[210:213], v[76:79]
	v_mfma_f32_16x16x32_bf16 v[72:75], v[152:155], v[210:213], v[72:75]
	v_mfma_f32_16x16x32_bf16 v[124:127], v[148:151], v[188:191], v[124:127]
	v_mfma_f32_16x16x32_bf16 v[120:123], v[156:159], v[188:191], v[120:123]
	v_mfma_f32_16x16x32_bf16 v[108:111], v[148:151], v[198:201], v[108:111]
	v_mfma_f32_16x16x32_bf16 v[104:107], v[156:159], v[198:201], v[104:107]
	v_mfma_f32_16x16x32_bf16 v[92:95], v[148:151], v[206:209], v[92:95]
	v_mfma_f32_16x16x32_bf16 v[88:91], v[156:159], v[206:209], v[88:91]
	v_mfma_f32_16x16x32_bf16 v[76:79], v[148:151], v[214:217], v[76:79]
	v_mfma_f32_16x16x32_bf16 v[72:75], v[156:159], v[214:217], v[72:75]
	v_mfma_f32_16x16x32_bf16 v[116:119], v[160:163], v[184:187], v[116:119]
	v_mfma_f32_16x16x32_bf16 v[112:115], v[168:171], v[184:187], v[112:115]
	v_mfma_f32_16x16x32_bf16 v[100:103], v[160:163], v[194:197], v[100:103]
	v_mfma_f32_16x16x32_bf16 v[96:99], v[168:171], v[194:197], v[96:99]
	v_mfma_f32_16x16x32_bf16 v[84:87], v[160:163], v[202:205], v[84:87]
	v_mfma_f32_16x16x32_bf16 v[80:83], v[168:171], v[202:205], v[80:83]
	v_mfma_f32_16x16x32_bf16 v[68:71], v[160:163], v[210:213], v[68:71]
	v_mfma_f32_16x16x32_bf16 v[64:67], v[168:171], v[210:213], v[64:67]
	v_mfma_f32_16x16x32_bf16 v[116:119], v[164:167], v[188:191], v[116:119]
	v_mfma_f32_16x16x32_bf16 v[112:115], v[180:183], v[188:191], v[112:115]
	v_mfma_f32_16x16x32_bf16 v[100:103], v[164:167], v[198:201], v[100:103]
	v_mfma_f32_16x16x32_bf16 v[96:99], v[180:183], v[198:201], v[96:99]
	v_mfma_f32_16x16x32_bf16 v[84:87], v[164:167], v[206:209], v[84:87]
	v_mfma_f32_16x16x32_bf16 v[80:83], v[180:183], v[206:209], v[80:83]
	v_mfma_f32_16x16x32_bf16 v[68:71], v[164:167], v[214:217], v[68:71]
	v_mfma_f32_16x16x32_bf16 v[64:67], v[180:183], v[214:217], v[64:67]
	s_setprio 0
	s_barrier
	s_add_u32 s4, s16, 0x8000
	s_addc_u32 s5, s14, 0
	s_mov_b32 m0, s73
	s_and_b32 s5, s5, 0xffff
	ds_read_b128 v[184:187], v144 offset:49152
	ds_read_b128 v[188:191], v144 offset:50176
	ds_read_b128 v[194:197], v144 offset:51200
	ds_read_b128 v[198:201], v144 offset:52224
	ds_read_b128 v[202:205], v144 offset:53248
	ds_read_b128 v[206:209], v144 offset:54272
	ds_read_b128 v[210:213], v144 offset:55296
	ds_read_b128 v[214:217], v144 offset:56320
	buffer_load_dwordx4 v129, s[4:7], 0 offen lds
	s_mov_b32 m0, s74
	s_mov_b32 s15, s7
	buffer_load_dwordx4 v131, s[4:7], 0 offen lds
	s_add_u32 s4, s16, 0xc000
	s_addc_u32 s5, s14, 0
	s_and_b32 s5, s5, 0xffff
	s_mov_b32 m0, s77
	s_and_b32 s13, s13, 0xffff
	buffer_load_dwordx4 v129, s[4:7], 0 offen lds
	s_mov_b32 m0, s78
	s_mov_b32 s14, s6
	buffer_load_dwordx4 v131, s[4:7], 0 offen lds
	s_mov_b32 m0, s75
	s_nop 0
	buffer_load_dwordx4 v128, s[12:15], 0 offen lds
	s_mov_b32 m0, s76
	s_nop 0
	buffer_load_dwordx4 v130, s[12:15], 0 offen lds
	s_waitcnt vmcnt(8)
	s_waitcnt lgkmcnt(0)
	s_barrier
	s_setprio 1
	v_mfma_f32_16x16x32_bf16 v[60:63], v[136:139], v[184:187], v[60:63]
	v_mfma_f32_16x16x32_bf16 v[56:59], v[152:155], v[184:187], v[56:59]
	v_mfma_f32_16x16x32_bf16 v[44:47], v[136:139], v[194:197], v[44:47]
	v_mfma_f32_16x16x32_bf16 v[40:43], v[152:155], v[194:197], v[40:43]
	v_mfma_f32_16x16x32_bf16 v[28:31], v[136:139], v[202:205], v[28:31]
	v_mfma_f32_16x16x32_bf16 v[24:27], v[152:155], v[202:205], v[24:27]
	v_mfma_f32_16x16x32_bf16 v[12:15], v[136:139], v[210:213], v[12:15]
	v_mfma_f32_16x16x32_bf16 v[8:11], v[152:155], v[210:213], v[8:11]
	v_mfma_f32_16x16x32_bf16 v[60:63], v[148:151], v[188:191], v[60:63]
	v_mfma_f32_16x16x32_bf16 v[56:59], v[156:159], v[188:191], v[56:59]
	v_mfma_f32_16x16x32_bf16 v[44:47], v[148:151], v[198:201], v[44:47]
	v_mfma_f32_16x16x32_bf16 v[40:43], v[156:159], v[198:201], v[40:43]
	v_mfma_f32_16x16x32_bf16 v[28:31], v[148:151], v[206:209], v[28:31]
	v_mfma_f32_16x16x32_bf16 v[24:27], v[156:159], v[206:209], v[24:27]
	v_mfma_f32_16x16x32_bf16 v[12:15], v[148:151], v[214:217], v[12:15]
	v_mfma_f32_16x16x32_bf16 v[8:11], v[156:159], v[214:217], v[8:11]
	v_mfma_f32_16x16x32_bf16 v[52:55], v[160:163], v[184:187], v[52:55]
	v_mfma_f32_16x16x32_bf16 v[48:51], v[168:171], v[184:187], v[48:51]
	v_mfma_f32_16x16x32_bf16 v[36:39], v[160:163], v[194:197], v[36:39]
	v_mfma_f32_16x16x32_bf16 v[32:35], v[168:171], v[194:197], v[32:35]
	v_mfma_f32_16x16x32_bf16 v[20:23], v[160:163], v[202:205], v[20:23]
	v_mfma_f32_16x16x32_bf16 v[16:19], v[168:171], v[202:205], v[16:19]
	v_mfma_f32_16x16x32_bf16 v[4:7], v[160:163], v[210:213], v[4:7]
	v_mfma_f32_16x16x32_bf16 v[0:3], v[168:171], v[210:213], v[0:3]
	v_mfma_f32_16x16x32_bf16 v[52:55], v[164:167], v[188:191], v[52:55]
	v_mfma_f32_16x16x32_bf16 v[48:51], v[180:183], v[188:191], v[48:51]
	v_mfma_f32_16x16x32_bf16 v[36:39], v[164:167], v[198:201], v[36:39]
	v_mfma_f32_16x16x32_bf16 v[32:35], v[180:183], v[198:201], v[32:35]
	v_mfma_f32_16x16x32_bf16 v[20:23], v[164:167], v[206:209], v[20:23]
	v_mfma_f32_16x16x32_bf16 v[16:19], v[180:183], v[206:209], v[16:19]
	v_mfma_f32_16x16x32_bf16 v[4:7], v[164:167], v[214:217], v[4:7]
	v_mfma_f32_16x16x32_bf16 v[0:3], v[180:183], v[214:217], v[0:3]
	s_setprio 0
	s_barrier
	s_add_i32 s64, s64, 2
	s_add_u32 s89, s89, 0x10000
	s_addc_u32 s90, s90, 0
	s_add_u32 s91, s91, 0x100
	s_addc_u32 s92, s92, 0
	s_cmpk_gt_u32 s64, 0xa9
	s_cbranch_scc0 .LBB0_935
	s_and_b64 vcc, exec, s[30:31]
	s_cbranch_vccz .LBB0_938
	s_barrier
